# GEMM K-loops: MFMA order 0,1,3,2,6,7,5,4 within each 8-group (operand shared between every adjacent pair)
# baseline (speedup 1.0000x reference)
.LBB0_383:
	s_ashr_i32 s67, s66, 31
	s_lshl_b64 s[26:27], s[66:67], 19
	s_add_u32 s26, s40, s26
	s_addc_u32 s27, s41, s27
	s_and_b64 s[34:35], s[8:9], exec
	s_cselect_b32 s34, s27, s5
	s_cselect_b32 s35, s26, s4
	s_ashr_i32 s29, s28, 31
	s_lshl_b64 s[38:39], s[28:29], 19
	s_add_u32 s62, s10, s38
	s_addc_u32 s63, s11, s39
	s_and_b64 s[38:39], s[8:9], exec
	s_cselect_b32 s29, s63, s83
	s_cselect_b32 s38, s62, s82
	s_add_u32 s39, s82, 0x100
	s_addc_u32 s67, s83, 0
	s_mov_b32 s94, -2
	s_mov_b64 vcc, 0
	v_lshl_add_u64 v[132:133], s[4:5], 0, v[168:169]
	ds_read_b128 v[134:137], v199
	ds_read_b128 v[138:141], v200
	ds_read_b128 v[142:145], v201
	ds_read_b128 v[146:149], v202
	ds_read_b128 v[150:153], v203
	ds_read_b128 v[174:177], v204
	ds_read_b128 v[178:181], v205
	ds_read_b128 v[182:185], v206
	s_add_u32 s24, s4, vcc_lo
	s_addc_u32 s25, s5, vcc_hi
	s_add_u32 s24, s24, 0x100
	s_addc_u32 s25, s25, 0
	s_add_u32 s82, s39, vcc_lo
	s_addc_u32 s83, s67, vcc_hi
	s_cmpk_eq_i32 vcc_lo, 0x700
	s_cselect_b32 s87, s29, s83
	s_cselect_b32 s86, s38, s82
	s_cselect_b32 s83, s34, s25
	s_cselect_b32 s82, s35, s24
	v_lshl_add_u64 v[154:155], v[132:133], 0, vcc
	v_lshl_add_u64 v[250:251], v[154:155], 0, s[48:49]
	s_add_i32 m0, s79, 0x8000
	s_mov_b64 s[24:25], 0x20080
	ds_read_b128 v[218:221], v207
	ds_read_b128 v[222:225], v207 offset:2048
	ds_read_b128 v[226:229], v208
	ds_read_b128 v[230:233], v208 offset:2048
	ds_read_b128 v[234:237], v207 offset:4096
	ds_read_b128 v[238:241], v207 offset:6144
	ds_read_b128 v[242:245], v208 offset:4096
	ds_read_b128 v[246:249], v208 offset:6144
	global_load_lds_dwordx4 v[250:251], off
	v_lshl_add_u64 v[250:251], v[154:155], 0, s[24:25]
	s_add_i32 m0, s79, 0xa000
	s_mov_b64 s[24:25], 0x60080
	global_load_lds_dwordx4 v[250:251], off
	v_lshl_add_u64 v[250:251], v[154:155], 0, s[50:51]
	s_add_i32 m0, s79, 0xc000
	v_lshl_add_u64 v[154:155], v[154:155], 0, s[24:25]
	global_load_lds_dwordx4 v[250:251], off
	s_add_i32 m0, s79, 0xe000
	s_nop 0
	global_load_lds_dwordx4 v[154:155], off
	s_waitcnt lgkmcnt(0)
	s_barrier
	v_mfma_f32_16x16x32_bf16 v[128:131], v[134:137], v[218:221], 0
	v_mfma_f32_16x16x32_bf16 v[124:127], v[142:145], v[218:221], 0
	v_mfma_f32_16x16x32_bf16 v[108:111], v[142:145], v[222:225], 0
	v_mfma_f32_16x16x32_bf16 v[112:115], v[134:137], v[222:225], 0
	v_mfma_f32_16x16x32_bf16 v[80:83], v[134:137], v[238:241], 0
	v_mfma_f32_16x16x32_bf16 v[76:79], v[142:145], v[238:241], 0
	v_mfma_f32_16x16x32_bf16 v[92:95], v[142:145], v[234:237], 0
	v_mfma_f32_16x16x32_bf16 v[96:99], v[134:137], v[234:237], 0
	v_mfma_f32_16x16x32_bf16 v[128:131], v[138:141], v[226:229], v[128:131]
	v_mfma_f32_16x16x32_bf16 v[124:127], v[146:149], v[226:229], v[124:127]
	v_mfma_f32_16x16x32_bf16 v[108:111], v[146:149], v[230:233], v[108:111]
	v_mfma_f32_16x16x32_bf16 v[112:115], v[138:141], v[230:233], v[112:115]
	v_mfma_f32_16x16x32_bf16 v[80:83], v[138:141], v[246:249], v[80:83]
	v_mfma_f32_16x16x32_bf16 v[76:79], v[146:149], v[246:249], v[76:79]
	v_mfma_f32_16x16x32_bf16 v[92:95], v[146:149], v[242:245], v[92:95]
	v_mfma_f32_16x16x32_bf16 v[96:99], v[138:141], v[242:245], v[96:99]
	v_mfma_f32_16x16x32_bf16 v[120:123], v[150:153], v[218:221], 0
	v_mfma_f32_16x16x32_bf16 v[116:119], v[178:181], v[218:221], 0
	v_mfma_f32_16x16x32_bf16 v[100:103], v[178:181], v[222:225], 0
	v_mfma_f32_16x16x32_bf16 v[104:107], v[150:153], v[222:225], 0
	v_mfma_f32_16x16x32_bf16 v[72:75], v[150:153], v[238:241], 0
	v_mfma_f32_16x16x32_bf16 v[68:71], v[178:181], v[238:241], 0
	v_mfma_f32_16x16x32_bf16 v[84:87], v[178:181], v[234:237], 0
	v_mfma_f32_16x16x32_bf16 v[88:91], v[150:153], v[234:237], 0
	v_mfma_f32_16x16x32_bf16 v[120:123], v[174:177], v[226:229], v[120:123]
	v_mfma_f32_16x16x32_bf16 v[116:119], v[182:185], v[226:229], v[116:119]
	v_mfma_f32_16x16x32_bf16 v[100:103], v[182:185], v[230:233], v[100:103]
	v_mfma_f32_16x16x32_bf16 v[104:107], v[174:177], v[230:233], v[104:107]
	v_mfma_f32_16x16x32_bf16 v[72:75], v[174:177], v[246:249], v[72:75]
	v_mfma_f32_16x16x32_bf16 v[68:71], v[182:185], v[246:249], v[68:71]
	v_mfma_f32_16x16x32_bf16 v[84:87], v[182:185], v[242:245], v[84:87]
	v_mfma_f32_16x16x32_bf16 v[88:91], v[174:177], v[242:245], v[88:91]
	s_barrier
	s_add_i32 s24, s1, s77
	v_lshl_add_u64 v[154:155], s[86:87], 0, v[158:159]
	s_mov_b32 m0, s24
	ds_read_b128 v[218:221], v207 offset:16384
	ds_read_b128 v[222:225], v207 offset:18432
	ds_read_b128 v[226:229], v208 offset:16384
	ds_read_b128 v[230:233], v208 offset:18432
	ds_read_b128 v[234:237], v207 offset:20480
	ds_read_b128 v[238:241], v207 offset:22528
	ds_read_b128 v[242:245], v208 offset:20480
	ds_read_b128 v[246:249], v208 offset:22528
	global_load_lds_dwordx4 v[154:155], off
	v_lshl_add_u64 v[250:251], v[154:155], 0, s[14:15]
	s_add_i32 m0, s24, 0x2000
	s_add_i32 s24, s12, s77
	global_load_lds_dwordx4 v[250:251], off
	v_lshl_add_u64 v[250:251], v[154:155], 0, s[16:17]
	s_mov_b32 m0, s24
	s_nop 0
	global_load_lds_dwordx4 v[250:251], off
	v_lshl_add_u64 v[250:251], v[154:155], 0, s[18:19]
	s_add_i32 m0, s24, 0x2000
	s_nop 0
	global_load_lds_dwordx4 v[250:251], off
	s_waitcnt vmcnt(4)
	s_waitcnt lgkmcnt(0)
	s_barrier
	v_mfma_f32_16x16x32_bf16 v[64:67], v[134:137], v[218:221], 0
	v_mfma_f32_16x16x32_bf16 v[60:63], v[142:145], v[218:221], 0
	v_mfma_f32_16x16x32_bf16 v[44:47], v[142:145], v[222:225], 0
	v_mfma_f32_16x16x32_bf16 v[48:51], v[134:137], v[222:225], 0
	v_mfma_f32_16x16x32_bf16 v[16:19], v[134:137], v[238:241], 0
	v_mfma_f32_16x16x32_bf16 v[12:15], v[142:145], v[238:241], 0
	v_mfma_f32_16x16x32_bf16 v[28:31], v[142:145], v[234:237], 0
	v_mfma_f32_16x16x32_bf16 v[32:35], v[134:137], v[234:237], 0
	v_mfma_f32_16x16x32_bf16 v[64:67], v[138:141], v[226:229], v[64:67]
	v_mfma_f32_16x16x32_bf16 v[60:63], v[146:149], v[226:229], v[60:63]
	v_mfma_f32_16x16x32_bf16 v[44:47], v[146:149], v[230:233], v[44:47]
	v_mfma_f32_16x16x32_bf16 v[48:51], v[138:141], v[230:233], v[48:51]
	v_mfma_f32_16x16x32_bf16 v[16:19], v[138:141], v[246:249], v[16:19]
	v_mfma_f32_16x16x32_bf16 v[12:15], v[146:149], v[246:249], v[12:15]
	v_mfma_f32_16x16x32_bf16 v[28:31], v[146:149], v[242:245], v[28:31]
	v_mfma_f32_16x16x32_bf16 v[32:35], v[138:141], v[242:245], v[32:35]
	v_mfma_f32_16x16x32_bf16 v[56:59], v[150:153], v[218:221], 0
	v_mfma_f32_16x16x32_bf16 v[52:55], v[178:181], v[218:221], 0
	v_mfma_f32_16x16x32_bf16 v[36:39], v[178:181], v[222:225], 0
	v_mfma_f32_16x16x32_bf16 v[40:43], v[150:153], v[222:225], 0
	v_mfma_f32_16x16x32_bf16 v[8:11], v[150:153], v[238:241], 0
	v_mfma_f32_16x16x32_bf16 v[4:7], v[178:181], v[238:241], 0
	v_mfma_f32_16x16x32_bf16 v[20:23], v[178:181], v[234:237], 0
	v_mfma_f32_16x16x32_bf16 v[24:27], v[150:153], v[234:237], 0
	v_mfma_f32_16x16x32_bf16 v[56:59], v[174:177], v[226:229], v[56:59]
	v_mfma_f32_16x16x32_bf16 v[52:55], v[182:185], v[226:229], v[52:55]
	v_mfma_f32_16x16x32_bf16 v[36:39], v[182:185], v[230:233], v[36:39]
	v_mfma_f32_16x16x32_bf16 v[40:43], v[174:177], v[230:233], v[40:43]
	v_mfma_f32_16x16x32_bf16 v[8:11], v[174:177], v[246:249], v[8:11]
	v_mfma_f32_16x16x32_bf16 v[4:7], v[182:185], v[246:249], v[4:7]
	v_mfma_f32_16x16x32_bf16 v[20:23], v[182:185], v[242:245], v[20:23]
	v_mfma_f32_16x16x32_bf16 v[24:27], v[174:177], v[242:245], v[24:27]
	s_barrier
	ds_read_b128 v[134:137], v213
	ds_read_b128 v[138:141], v214
	ds_read_b128 v[142:145], v209
	ds_read_b128 v[146:149], v210
	ds_read_b128 v[150:153], v215
	ds_read_b128 v[174:177], v216
	ds_read_b128 v[178:181], v211
	ds_read_b128 v[182:185], v212
	s_mov_b32 m0, s79
	v_lshl_add_u64 v[250:251], s[82:83], 0, v[0:1]
	ds_read_b128 v[218:221], v207 offset:32768
	ds_read_b128 v[222:225], v207 offset:34816
	ds_read_b128 v[226:229], v208 offset:32768
	ds_read_b128 v[230:233], v208 offset:34816
	ds_read_b128 v[234:237], v207 offset:36864
	ds_read_b128 v[238:241], v207 offset:38912
	ds_read_b128 v[242:245], v208 offset:36864
	ds_read_b128 v[246:249], v208 offset:38912
	global_load_lds_dwordx4 v[250:251], off
	v_lshl_add_u64 v[252:253], v[250:251], 0, s[20:21]
	s_mov_b32 m0, s81
	s_nop 0
	global_load_lds_dwordx4 v[252:253], off
	v_lshl_add_u64 v[252:253], v[250:251], 0, s[14:15]
	s_mov_b32 m0, s97
	v_lshl_add_u64 v[250:251], v[250:251], 0, s[22:23]
	global_load_lds_dwordx4 v[252:253], off
	s_mov_b32 m0, s64
	s_nop 0
	global_load_lds_dwordx4 v[250:251], off
	s_waitcnt vmcnt(8)
	s_waitcnt lgkmcnt(0)
	s_barrier
	v_mfma_f32_16x16x32_bf16 v[128:131], v[134:137], v[218:221], v[128:131]
	v_mfma_f32_16x16x32_bf16 v[124:127], v[142:145], v[218:221], v[124:127]
	v_mfma_f32_16x16x32_bf16 v[108:111], v[142:145], v[222:225], v[108:111]
	v_mfma_f32_16x16x32_bf16 v[112:115], v[134:137], v[222:225], v[112:115]
	v_mfma_f32_16x16x32_bf16 v[80:83], v[134:137], v[238:241], v[80:83]
	v_mfma_f32_16x16x32_bf16 v[76:79], v[142:145], v[238:241], v[76:79]
	v_mfma_f32_16x16x32_bf16 v[92:95], v[142:145], v[234:237], v[92:95]
	v_mfma_f32_16x16x32_bf16 v[96:99], v[134:137], v[234:237], v[96:99]
	v_mfma_f32_16x16x32_bf16 v[128:131], v[138:141], v[226:229], v[128:131]
	v_mfma_f32_16x16x32_bf16 v[124:127], v[146:149], v[226:229], v[124:127]
	v_mfma_f32_16x16x32_bf16 v[108:111], v[146:149], v[230:233], v[108:111]
	v_mfma_f32_16x16x32_bf16 v[112:115], v[138:141], v[230:233], v[112:115]
	v_mfma_f32_16x16x32_bf16 v[80:83], v[138:141], v[246:249], v[80:83]
	v_mfma_f32_16x16x32_bf16 v[76:79], v[146:149], v[246:249], v[76:79]
	v_mfma_f32_16x16x32_bf16 v[92:95], v[146:149], v[242:245], v[92:95]
	v_mfma_f32_16x16x32_bf16 v[96:99], v[138:141], v[242:245], v[96:99]
	v_mfma_f32_16x16x32_bf16 v[120:123], v[150:153], v[218:221], v[120:123]
	v_mfma_f32_16x16x32_bf16 v[116:119], v[178:181], v[218:221], v[116:119]
	v_mfma_f32_16x16x32_bf16 v[100:103], v[178:181], v[222:225], v[100:103]
	v_mfma_f32_16x16x32_bf16 v[104:107], v[150:153], v[222:225], v[104:107]
	v_mfma_f32_16x16x32_bf16 v[72:75], v[150:153], v[238:241], v[72:75]
	v_mfma_f32_16x16x32_bf16 v[68:71], v[178:181], v[238:241], v[68:71]
	v_mfma_f32_16x16x32_bf16 v[84:87], v[178:181], v[234:237], v[84:87]
	v_mfma_f32_16x16x32_bf16 v[88:91], v[150:153], v[234:237], v[88:91]
	v_mfma_f32_16x16x32_bf16 v[120:123], v[174:177], v[226:229], v[120:123]
	v_mfma_f32_16x16x32_bf16 v[116:119], v[182:185], v[226:229], v[116:119]
	v_mfma_f32_16x16x32_bf16 v[100:103], v[182:185], v[230:233], v[100:103]
	v_mfma_f32_16x16x32_bf16 v[104:107], v[174:177], v[230:233], v[104:107]
	v_mfma_f32_16x16x32_bf16 v[72:75], v[174:177], v[246:249], v[72:75]
	v_mfma_f32_16x16x32_bf16 v[68:71], v[182:185], v[246:249], v[68:71]
	v_mfma_f32_16x16x32_bf16 v[84:87], v[182:185], v[242:245], v[84:87]
	v_mfma_f32_16x16x32_bf16 v[88:91], v[174:177], v[242:245], v[88:91]
	s_barrier
	s_add_i32 s24, s70, s77
	v_lshl_add_u64 v[250:251], v[154:155], 0, s[48:49]
	s_mov_b32 m0, s24
	ds_read_b128 v[218:221], v207 offset:49152
	ds_read_b128 v[222:225], v207 offset:51200
	ds_read_b128 v[226:229], v208 offset:49152
	ds_read_b128 v[230:233], v208 offset:51200
	ds_read_b128 v[234:237], v207 offset:53248
	ds_read_b128 v[238:241], v207 offset:55296
	ds_read_b128 v[242:245], v208 offset:53248
	ds_read_b128 v[246:249], v208 offset:55296
	global_load_lds_dwordx4 v[250:251], off
	v_lshl_add_u64 v[250:251], v[154:155], 0, s[50:51]
	s_add_i32 m0, s24, 0x2000
	s_add_i32 s24, s71, s77
	global_load_lds_dwordx4 v[250:251], off
	v_lshl_add_u64 v[250:251], v[154:155], 0, s[52:53]
	s_mov_b32 m0, s24
	v_lshl_add_u64 v[154:155], v[154:155], 0, s[54:55]
	global_load_lds_dwordx4 v[250:251], off
	s_add_i32 m0, s24, 0x2000
	s_nop 0
	global_load_lds_dwordx4 v[154:155], off
	s_waitcnt vmcnt(4)
	s_waitcnt lgkmcnt(0)
	s_barrier
	v_mfma_f32_16x16x32_bf16 v[64:67], v[134:137], v[218:221], v[64:67]
	v_mfma_f32_16x16x32_bf16 v[60:63], v[142:145], v[218:221], v[60:63]
	v_mfma_f32_16x16x32_bf16 v[44:47], v[142:145], v[222:225], v[44:47]
	v_mfma_f32_16x16x32_bf16 v[48:51], v[134:137], v[222:225], v[48:51]
	v_mfma_f32_16x16x32_bf16 v[16:19], v[134:137], v[238:241], v[16:19]
	v_mfma_f32_16x16x32_bf16 v[12:15], v[142:145], v[238:241], v[12:15]
	v_mfma_f32_16x16x32_bf16 v[28:31], v[142:145], v[234:237], v[28:31]
	v_mfma_f32_16x16x32_bf16 v[32:35], v[134:137], v[234:237], v[32:35]
	v_mfma_f32_16x16x32_bf16 v[64:67], v[138:141], v[226:229], v[64:67]
	v_mfma_f32_16x16x32_bf16 v[60:63], v[146:149], v[226:229], v[60:63]
	v_mfma_f32_16x16x32_bf16 v[44:47], v[146:149], v[230:233], v[44:47]
	v_mfma_f32_16x16x32_bf16 v[48:51], v[138:141], v[230:233], v[48:51]
	v_mfma_f32_16x16x32_bf16 v[16:19], v[138:141], v[246:249], v[16:19]
	v_mfma_f32_16x16x32_bf16 v[12:15], v[146:149], v[246:249], v[12:15]
	v_mfma_f32_16x16x32_bf16 v[28:31], v[146:149], v[242:245], v[28:31]
	v_mfma_f32_16x16x32_bf16 v[32:35], v[138:141], v[242:245], v[32:35]
	v_mfma_f32_16x16x32_bf16 v[56:59], v[150:153], v[218:221], v[56:59]
	v_mfma_f32_16x16x32_bf16 v[52:55], v[178:181], v[218:221], v[52:55]
	v_mfma_f32_16x16x32_bf16 v[36:39], v[178:181], v[222:225], v[36:39]
	v_mfma_f32_16x16x32_bf16 v[40:43], v[150:153], v[222:225], v[40:43]
	v_mfma_f32_16x16x32_bf16 v[8:11], v[150:153], v[238:241], v[8:11]
	v_mfma_f32_16x16x32_bf16 v[4:7], v[178:181], v[238:241], v[4:7]
	v_mfma_f32_16x16x32_bf16 v[20:23], v[178:181], v[234:237], v[20:23]
	v_mfma_f32_16x16x32_bf16 v[24:27], v[150:153], v[234:237], v[24:27]
	v_mfma_f32_16x16x32_bf16 v[56:59], v[174:177], v[226:229], v[56:59]
	v_mfma_f32_16x16x32_bf16 v[52:55], v[182:185], v[226:229], v[52:55]
	v_mfma_f32_16x16x32_bf16 v[36:39], v[182:185], v[230:233], v[36:39]
	v_mfma_f32_16x16x32_bf16 v[40:43], v[174:177], v[230:233], v[40:43]
	v_mfma_f32_16x16x32_bf16 v[8:11], v[174:177], v[246:249], v[8:11]
	v_mfma_f32_16x16x32_bf16 v[4:7], v[182:185], v[246:249], v[4:7]
	v_mfma_f32_16x16x32_bf16 v[20:23], v[182:185], v[242:245], v[20:23]
	v_mfma_f32_16x16x32_bf16 v[24:27], v[174:177], v[242:245], v[24:27]
	s_barrier
	s_add_i32 s94, s94, 2
	s_add_u32 vcc_lo, vcc_lo, 0x100
	s_addc_u32 vcc_hi, vcc_hi, 0
	s_cmp_gt_u32 s94, 13
.LBB0_384:
	ds_read_b128 v[134:137], v199
	ds_read_b128 v[138:141], v200
	ds_read_b128 v[142:145], v201
	ds_read_b128 v[146:149], v202
	ds_read_b128 v[150:153], v203
	ds_read_b128 v[174:177], v204
	ds_read_b128 v[178:181], v205
	ds_read_b128 v[182:185], v206
	s_add_u32 s24, s4, vcc_lo
	s_addc_u32 s25, s5, vcc_hi
	s_add_u32 s24, s24, 0x100
	s_addc_u32 s25, s25, 0
	s_add_u32 s82, s39, vcc_lo
	s_addc_u32 s83, s67, vcc_hi
	s_cmpk_eq_i32 vcc_lo, 0x700
	s_cselect_b32 s87, s29, s83
	s_cselect_b32 s86, s38, s82
	s_cselect_b32 s83, s34, s25
	s_cselect_b32 s82, s35, s24
	v_lshl_add_u64 v[154:155], v[132:133], 0, vcc
	v_lshl_add_u64 v[250:251], v[154:155], 0, s[48:49]
	s_add_i32 m0, s79, 0x8000
	s_mov_b64 s[24:25], 0x20080
	ds_read_b128 v[218:221], v207
	ds_read_b128 v[222:225], v207 offset:2048
	ds_read_b128 v[226:229], v208
	ds_read_b128 v[230:233], v208 offset:2048
	ds_read_b128 v[234:237], v207 offset:4096
	ds_read_b128 v[238:241], v207 offset:6144
	ds_read_b128 v[242:245], v208 offset:4096
	ds_read_b128 v[246:249], v208 offset:6144
	global_load_lds_dwordx4 v[250:251], off
	v_lshl_add_u64 v[250:251], v[154:155], 0, s[24:25]
	s_add_i32 m0, s79, 0xa000
	s_mov_b64 s[24:25], 0x60080
	global_load_lds_dwordx4 v[250:251], off
	v_lshl_add_u64 v[250:251], v[154:155], 0, s[50:51]
	s_add_i32 m0, s79, 0xc000
	v_lshl_add_u64 v[154:155], v[154:155], 0, s[24:25]
	global_load_lds_dwordx4 v[250:251], off
	s_add_i32 m0, s79, 0xe000
	s_nop 0
	global_load_lds_dwordx4 v[154:155], off
	s_waitcnt vmcnt(8)
	s_waitcnt lgkmcnt(0)
	s_barrier
	v_mfma_f32_16x16x32_bf16 v[128:131], v[134:137], v[218:221], v[128:131]
	v_mfma_f32_16x16x32_bf16 v[124:127], v[142:145], v[218:221], v[124:127]
	v_mfma_f32_16x16x32_bf16 v[108:111], v[142:145], v[222:225], v[108:111]
	v_mfma_f32_16x16x32_bf16 v[112:115], v[134:137], v[222:225], v[112:115]
	v_mfma_f32_16x16x32_bf16 v[80:83], v[134:137], v[238:241], v[80:83]
	v_mfma_f32_16x16x32_bf16 v[76:79], v[142:145], v[238:241], v[76:79]
	v_mfma_f32_16x16x32_bf16 v[92:95], v[142:145], v[234:237], v[92:95]
	v_mfma_f32_16x16x32_bf16 v[96:99], v[134:137], v[234:237], v[96:99]
	v_mfma_f32_16x16x32_bf16 v[128:131], v[138:141], v[226:229], v[128:131]
	v_mfma_f32_16x16x32_bf16 v[124:127], v[146:149], v[226:229], v[124:127]
	v_mfma_f32_16x16x32_bf16 v[108:111], v[146:149], v[230:233], v[108:111]
	v_mfma_f32_16x16x32_bf16 v[112:115], v[138:141], v[230:233], v[112:115]
	v_mfma_f32_16x16x32_bf16 v[80:83], v[138:141], v[246:249], v[80:83]
	v_mfma_f32_16x16x32_bf16 v[76:79], v[146:149], v[246:249], v[76:79]
	v_mfma_f32_16x16x32_bf16 v[92:95], v[146:149], v[242:245], v[92:95]
	v_mfma_f32_16x16x32_bf16 v[96:99], v[138:141], v[242:245], v[96:99]
	v_mfma_f32_16x16x32_bf16 v[120:123], v[150:153], v[218:221], v[120:123]
	v_mfma_f32_16x16x32_bf16 v[116:119], v[178:181], v[218:221], v[116:119]
	v_mfma_f32_16x16x32_bf16 v[100:103], v[178:181], v[222:225], v[100:103]
	v_mfma_f32_16x16x32_bf16 v[104:107], v[150:153], v[222:225], v[104:107]
	v_mfma_f32_16x16x32_bf16 v[72:75], v[150:153], v[238:241], v[72:75]
	v_mfma_f32_16x16x32_bf16 v[68:71], v[178:181], v[238:241], v[68:71]
	v_mfma_f32_16x16x32_bf16 v[84:87], v[178:181], v[234:237], v[84:87]
	v_mfma_f32_16x16x32_bf16 v[88:91], v[150:153], v[234:237], v[88:91]
	v_mfma_f32_16x16x32_bf16 v[120:123], v[174:177], v[226:229], v[120:123]
	v_mfma_f32_16x16x32_bf16 v[116:119], v[182:185], v[226:229], v[116:119]
	v_mfma_f32_16x16x32_bf16 v[100:103], v[182:185], v[230:233], v[100:103]
	v_mfma_f32_16x16x32_bf16 v[104:107], v[174:177], v[230:233], v[104:107]
	v_mfma_f32_16x16x32_bf16 v[72:75], v[174:177], v[246:249], v[72:75]
	v_mfma_f32_16x16x32_bf16 v[68:71], v[182:185], v[246:249], v[68:71]
	v_mfma_f32_16x16x32_bf16 v[84:87], v[182:185], v[242:245], v[84:87]
	v_mfma_f32_16x16x32_bf16 v[88:91], v[174:177], v[242:245], v[88:91]
	s_barrier
	s_add_i32 s24, s1, s77
	v_lshl_add_u64 v[154:155], s[86:87], 0, v[158:159]
	s_mov_b32 m0, s24
	ds_read_b128 v[218:221], v207 offset:16384
	ds_read_b128 v[222:225], v207 offset:18432
	ds_read_b128 v[226:229], v208 offset:16384
	ds_read_b128 v[230:233], v208 offset:18432
	ds_read_b128 v[234:237], v207 offset:20480
	ds_read_b128 v[238:241], v207 offset:22528
	ds_read_b128 v[242:245], v208 offset:20480
	ds_read_b128 v[246:249], v208 offset:22528
	global_load_lds_dwordx4 v[154:155], off
	v_lshl_add_u64 v[250:251], v[154:155], 0, s[14:15]
	s_add_i32 m0, s24, 0x2000
	s_add_i32 s24, s12, s77
	global_load_lds_dwordx4 v[250:251], off
	v_lshl_add_u64 v[250:251], v[154:155], 0, s[16:17]
	s_mov_b32 m0, s24
	s_nop 0
	global_load_lds_dwordx4 v[250:251], off
	v_lshl_add_u64 v[250:251], v[154:155], 0, s[18:19]
	s_add_i32 m0, s24, 0x2000
	s_nop 0
	global_load_lds_dwordx4 v[250:251], off
	s_waitcnt vmcnt(4)
	s_waitcnt lgkmcnt(0)
	s_barrier
	v_mfma_f32_16x16x32_bf16 v[64:67], v[134:137], v[218:221], v[64:67]
	v_mfma_f32_16x16x32_bf16 v[60:63], v[142:145], v[218:221], v[60:63]
	v_mfma_f32_16x16x32_bf16 v[44:47], v[142:145], v[222:225], v[44:47]
	v_mfma_f32_16x16x32_bf16 v[48:51], v[134:137], v[222:225], v[48:51]
	v_mfma_f32_16x16x32_bf16 v[16:19], v[134:137], v[238:241], v[16:19]
	v_mfma_f32_16x16x32_bf16 v[12:15], v[142:145], v[238:241], v[12:15]
	v_mfma_f32_16x16x32_bf16 v[28:31], v[142:145], v[234:237], v[28:31]
	v_mfma_f32_16x16x32_bf16 v[32:35], v[134:137], v[234:237], v[32:35]
	v_mfma_f32_16x16x32_bf16 v[64:67], v[138:141], v[226:229], v[64:67]
	v_mfma_f32_16x16x32_bf16 v[60:63], v[146:149], v[226:229], v[60:63]
	v_mfma_f32_16x16x32_bf16 v[44:47], v[146:149], v[230:233], v[44:47]
	v_mfma_f32_16x16x32_bf16 v[48:51], v[138:141], v[230:233], v[48:51]
	v_mfma_f32_16x16x32_bf16 v[16:19], v[138:141], v[246:249], v[16:19]
	v_mfma_f32_16x16x32_bf16 v[12:15], v[146:149], v[246:249], v[12:15]
	v_mfma_f32_16x16x32_bf16 v[28:31], v[146:149], v[242:245], v[28:31]
	v_mfma_f32_16x16x32_bf16 v[32:35], v[138:141], v[242:245], v[32:35]
	v_mfma_f32_16x16x32_bf16 v[56:59], v[150:153], v[218:221], v[56:59]
	v_mfma_f32_16x16x32_bf16 v[52:55], v[178:181], v[218:221], v[52:55]
	v_mfma_f32_16x16x32_bf16 v[36:39], v[178:181], v[222:225], v[36:39]
	v_mfma_f32_16x16x32_bf16 v[40:43], v[150:153], v[222:225], v[40:43]
	v_mfma_f32_16x16x32_bf16 v[8:11], v[150:153], v[238:241], v[8:11]
	v_mfma_f32_16x16x32_bf16 v[4:7], v[178:181], v[238:241], v[4:7]
	v_mfma_f32_16x16x32_bf16 v[20:23], v[178:181], v[234:237], v[20:23]
	v_mfma_f32_16x16x32_bf16 v[24:27], v[150:153], v[234:237], v[24:27]
	v_mfma_f32_16x16x32_bf16 v[56:59], v[174:177], v[226:229], v[56:59]
	v_mfma_f32_16x16x32_bf16 v[52:55], v[182:185], v[226:229], v[52:55]
	v_mfma_f32_16x16x32_bf16 v[36:39], v[182:185], v[230:233], v[36:39]
	v_mfma_f32_16x16x32_bf16 v[40:43], v[174:177], v[230:233], v[40:43]
	v_mfma_f32_16x16x32_bf16 v[8:11], v[174:177], v[246:249], v[8:11]
	v_mfma_f32_16x16x32_bf16 v[4:7], v[182:185], v[246:249], v[4:7]
	v_mfma_f32_16x16x32_bf16 v[20:23], v[182:185], v[242:245], v[20:23]
	v_mfma_f32_16x16x32_bf16 v[24:27], v[174:177], v[242:245], v[24:27]
	s_barrier
	ds_read_b128 v[134:137], v213
	ds_read_b128 v[138:141], v214
	ds_read_b128 v[142:145], v209
	ds_read_b128 v[146:149], v210
	ds_read_b128 v[150:153], v215
	ds_read_b128 v[174:177], v216
	ds_read_b128 v[178:181], v211
	ds_read_b128 v[182:185], v212
	s_mov_b32 m0, s79
	v_lshl_add_u64 v[250:251], s[82:83], 0, v[0:1]
	ds_read_b128 v[218:221], v207 offset:32768
	ds_read_b128 v[222:225], v207 offset:34816
	ds_read_b128 v[226:229], v208 offset:32768
	ds_read_b128 v[230:233], v208 offset:34816
	ds_read_b128 v[234:237], v207 offset:36864
	ds_read_b128 v[238:241], v207 offset:38912
	ds_read_b128 v[242:245], v208 offset:36864
	ds_read_b128 v[246:249], v208 offset:38912
	global_load_lds_dwordx4 v[250:251], off
	v_lshl_add_u64 v[252:253], v[250:251], 0, s[20:21]
	s_mov_b32 m0, s81
	s_nop 0
	global_load_lds_dwordx4 v[252:253], off
	v_lshl_add_u64 v[252:253], v[250:251], 0, s[14:15]
	s_mov_b32 m0, s97
	v_lshl_add_u64 v[250:251], v[250:251], 0, s[22:23]
	global_load_lds_dwordx4 v[252:253], off
	s_mov_b32 m0, s64
	s_nop 0
	global_load_lds_dwordx4 v[250:251], off
	s_waitcnt vmcnt(8)
	s_waitcnt lgkmcnt(0)
	s_barrier
	v_mfma_f32_16x16x32_bf16 v[128:131], v[134:137], v[218:221], v[128:131]
	v_mfma_f32_16x16x32_bf16 v[124:127], v[142:145], v[218:221], v[124:127]
	v_mfma_f32_16x16x32_bf16 v[108:111], v[142:145], v[222:225], v[108:111]
	v_mfma_f32_16x16x32_bf16 v[112:115], v[134:137], v[222:225], v[112:115]
	v_mfma_f32_16x16x32_bf16 v[80:83], v[134:137], v[238:241], v[80:83]
	v_mfma_f32_16x16x32_bf16 v[76:79], v[142:145], v[238:241], v[76:79]
	v_mfma_f32_16x16x32_bf16 v[92:95], v[142:145], v[234:237], v[92:95]
	v_mfma_f32_16x16x32_bf16 v[96:99], v[134:137], v[234:237], v[96:99]
	v_mfma_f32_16x16x32_bf16 v[128:131], v[138:141], v[226:229], v[128:131]
	v_mfma_f32_16x16x32_bf16 v[124:127], v[146:149], v[226:229], v[124:127]
	v_mfma_f32_16x16x32_bf16 v[108:111], v[146:149], v[230:233], v[108:111]
	v_mfma_f32_16x16x32_bf16 v[112:115], v[138:141], v[230:233], v[112:115]
	v_mfma_f32_16x16x32_bf16 v[80:83], v[138:141], v[246:249], v[80:83]
	v_mfma_f32_16x16x32_bf16 v[76:79], v[146:149], v[246:249], v[76:79]
	v_mfma_f32_16x16x32_bf16 v[92:95], v[146:149], v[242:245], v[92:95]
	v_mfma_f32_16x16x32_bf16 v[96:99], v[138:141], v[242:245], v[96:99]
	v_mfma_f32_16x16x32_bf16 v[120:123], v[150:153], v[218:221], v[120:123]
	v_mfma_f32_16x16x32_bf16 v[116:119], v[178:181], v[218:221], v[116:119]
	v_mfma_f32_16x16x32_bf16 v[100:103], v[178:181], v[222:225], v[100:103]
	v_mfma_f32_16x16x32_bf16 v[104:107], v[150:153], v[222:225], v[104:107]
	v_mfma_f32_16x16x32_bf16 v[72:75], v[150:153], v[238:241], v[72:75]
	v_mfma_f32_16x16x32_bf16 v[68:71], v[178:181], v[238:241], v[68:71]
	v_mfma_f32_16x16x32_bf16 v[84:87], v[178:181], v[234:237], v[84:87]
	v_mfma_f32_16x16x32_bf16 v[88:91], v[150:153], v[234:237], v[88:91]
	v_mfma_f32_16x16x32_bf16 v[120:123], v[174:177], v[226:229], v[120:123]
	v_mfma_f32_16x16x32_bf16 v[116:119], v[182:185], v[226:229], v[116:119]
	v_mfma_f32_16x16x32_bf16 v[100:103], v[182:185], v[230:233], v[100:103]
	v_mfma_f32_16x16x32_bf16 v[104:107], v[174:177], v[230:233], v[104:107]
	v_mfma_f32_16x16x32_bf16 v[72:75], v[174:177], v[246:249], v[72:75]
	v_mfma_f32_16x16x32_bf16 v[68:71], v[182:185], v[246:249], v[68:71]
	v_mfma_f32_16x16x32_bf16 v[84:87], v[182:185], v[242:245], v[84:87]
	v_mfma_f32_16x16x32_bf16 v[88:91], v[174:177], v[242:245], v[88:91]
	s_barrier
	s_add_i32 s24, s70, s77
	v_lshl_add_u64 v[250:251], v[154:155], 0, s[48:49]
	s_mov_b32 m0, s24
	ds_read_b128 v[218:221], v207 offset:49152
	ds_read_b128 v[222:225], v207 offset:51200
	ds_read_b128 v[226:229], v208 offset:49152
	ds_read_b128 v[230:233], v208 offset:51200
	ds_read_b128 v[234:237], v207 offset:53248
	ds_read_b128 v[238:241], v207 offset:55296
	ds_read_b128 v[242:245], v208 offset:53248
	ds_read_b128 v[246:249], v208 offset:55296
	global_load_lds_dwordx4 v[250:251], off
	v_lshl_add_u64 v[250:251], v[154:155], 0, s[50:51]
	s_add_i32 m0, s24, 0x2000
	s_add_i32 s24, s71, s77
	global_load_lds_dwordx4 v[250:251], off
	v_lshl_add_u64 v[250:251], v[154:155], 0, s[52:53]
	s_mov_b32 m0, s24
	v_lshl_add_u64 v[154:155], v[154:155], 0, s[54:55]
	global_load_lds_dwordx4 v[250:251], off
	s_add_i32 m0, s24, 0x2000
	s_nop 0
	global_load_lds_dwordx4 v[154:155], off
	s_waitcnt vmcnt(4)
	s_waitcnt lgkmcnt(0)
	s_barrier
	v_mfma_f32_16x16x32_bf16 v[64:67], v[134:137], v[218:221], v[64:67]
	v_mfma_f32_16x16x32_bf16 v[60:63], v[142:145], v[218:221], v[60:63]
	v_mfma_f32_16x16x32_bf16 v[44:47], v[142:145], v[222:225], v[44:47]
	v_mfma_f32_16x16x32_bf16 v[48:51], v[134:137], v[222:225], v[48:51]
	v_mfma_f32_16x16x32_bf16 v[16:19], v[134:137], v[238:241], v[16:19]
	v_mfma_f32_16x16x32_bf16 v[12:15], v[142:145], v[238:241], v[12:15]
	v_mfma_f32_16x16x32_bf16 v[28:31], v[142:145], v[234:237], v[28:31]
	v_mfma_f32_16x16x32_bf16 v[32:35], v[134:137], v[234:237], v[32:35]
	v_mfma_f32_16x16x32_bf16 v[64:67], v[138:141], v[226:229], v[64:67]
	v_mfma_f32_16x16x32_bf16 v[60:63], v[146:149], v[226:229], v[60:63]
	v_mfma_f32_16x16x32_bf16 v[44:47], v[146:149], v[230:233], v[44:47]
	v_mfma_f32_16x16x32_bf16 v[48:51], v[138:141], v[230:233], v[48:51]
	v_mfma_f32_16x16x32_bf16 v[16:19], v[138:141], v[246:249], v[16:19]
	v_mfma_f32_16x16x32_bf16 v[12:15], v[146:149], v[246:249], v[12:15]
	v_mfma_f32_16x16x32_bf16 v[28:31], v[146:149], v[242:245], v[28:31]
	v_mfma_f32_16x16x32_bf16 v[32:35], v[138:141], v[242:245], v[32:35]
	v_mfma_f32_16x16x32_bf16 v[56:59], v[150:153], v[218:221], v[56:59]
	v_mfma_f32_16x16x32_bf16 v[52:55], v[178:181], v[218:221], v[52:55]
	v_mfma_f32_16x16x32_bf16 v[36:39], v[178:181], v[222:225], v[36:39]
	v_mfma_f32_16x16x32_bf16 v[40:43], v[150:153], v[222:225], v[40:43]
	v_mfma_f32_16x16x32_bf16 v[8:11], v[150:153], v[238:241], v[8:11]
	v_mfma_f32_16x16x32_bf16 v[4:7], v[178:181], v[238:241], v[4:7]
	v_mfma_f32_16x16x32_bf16 v[20:23], v[178:181], v[234:237], v[20:23]
	v_mfma_f32_16x16x32_bf16 v[24:27], v[150:153], v[234:237], v[24:27]
	v_mfma_f32_16x16x32_bf16 v[56:59], v[174:177], v[226:229], v[56:59]
	v_mfma_f32_16x16x32_bf16 v[52:55], v[182:185], v[226:229], v[52:55]
	v_mfma_f32_16x16x32_bf16 v[36:39], v[182:185], v[230:233], v[36:39]
	v_mfma_f32_16x16x32_bf16 v[40:43], v[174:177], v[230:233], v[40:43]
	v_mfma_f32_16x16x32_bf16 v[8:11], v[174:177], v[246:249], v[8:11]
	v_mfma_f32_16x16x32_bf16 v[4:7], v[182:185], v[246:249], v[4:7]
	v_mfma_f32_16x16x32_bf16 v[20:23], v[182:185], v[242:245], v[20:23]
	v_mfma_f32_16x16x32_bf16 v[24:27], v[174:177], v[242:245], v[24:27]
	s_barrier
	s_add_i32 s94, s94, 2
	s_add_u32 vcc_lo, vcc_lo, 0x100
	s_addc_u32 vcc_hi, vcc_hi, 0
	s_cmp_gt_u32 s94, 13
	s_cbranch_scc0 .LBB0_384
	s_and_b64 vcc, exec, s[56:57]
	s_cbranch_vccz .LBB0_387
	s_barrier

.LBB0_779:
	v_add_u32_e32 v4, s73, v159
	v_add_u32_e32 v6, s73, v173
	ds_read_b128 v[136:139], v4
	ds_read_b128 v[140:143], v6
	v_add_u32_e32 v4, s77, v159
	s_add_u32 s26, s28, s64
	v_add_u32_e32 v6, s77, v173
	ds_read_b128 v[180:183], v4
	ds_read_b128 v[196:199], v6
	v_add_u32_e32 v4, s79, v159
	s_addc_u32 s27, s29, s65
	v_add_u32_e32 v6, s79, v173
	ds_read_b128 v[200:203], v4
	ds_read_b128 v[204:207], v6
	v_add_u32_e32 v4, s80, v159
	s_add_u32 s26, s26, 0x100
	v_add_u32_e32 v6, s80, v173
	ds_read_b128 v[208:211], v4
	ds_read_b128 v[212:215], v6
	s_addc_u32 s27, s27, 0
	s_add_u32 s34, s93, s64
	s_addc_u32 s35, s94, s65
	s_cmpk_eq_i32 s64, 0xb00
	s_cselect_b32 s35, s63, s35
	s_cselect_b32 s34, s62, s34
	s_cselect_b32 s27, s1, s27
	s_cselect_b32 s26, s0, s26
	v_lshl_add_u64 v[6:7], v[170:171], 0, s[64:65]
	v_lshl_add_u64 v[184:185], v[6:7], 0, s[24:25]
	s_add_i32 m0, s66, 0x8000
	s_mov_b64 s[38:39], 0x30080
	ds_read_b128 v[216:219], v176
	ds_read_b128 v[220:223], v176 offset:2048
	ds_read_b128 v[224:227], v177
	ds_read_b128 v[228:231], v177 offset:2048
	ds_read_b128 v[232:235], v176 offset:4096
	ds_read_b128 v[236:239], v176 offset:6144
	ds_read_b128 v[240:243], v177 offset:4096
	ds_read_b128 v[244:247], v177 offset:6144
	global_load_lds_dwordx4 v[184:185], off
	v_lshl_add_u64 v[184:185], v[6:7], 0, s[38:39]
	s_add_i32 m0, s66, 0xa000
	s_mov_b64 s[38:39], 0x90080
	global_load_lds_dwordx4 v[184:185], off
	v_lshl_add_u64 v[184:185], v[6:7], 0, s[50:51]
	s_add_i32 m0, s66, 0xc000
	v_lshl_add_u64 v[6:7], v[6:7], 0, s[38:39]
	global_load_lds_dwordx4 v[184:185], off
	s_add_i32 m0, s66, 0xe000
	s_nop 0
	global_load_lds_dwordx4 v[6:7], off
	s_waitcnt vmcnt(8)
	s_waitcnt lgkmcnt(0)
	s_barrier
	v_mfma_f32_16x16x32_bf16 v[132:135], v[136:139], v[216:219], v[132:135]
	v_mfma_f32_16x16x32_bf16 v[128:131], v[180:183], v[216:219], v[128:131]
	v_mfma_f32_16x16x32_bf16 v[112:115], v[180:183], v[220:223], v[112:115]
	v_mfma_f32_16x16x32_bf16 v[116:119], v[136:139], v[220:223], v[116:119]
	v_mfma_f32_16x16x32_bf16 v[84:87], v[136:139], v[236:239], v[84:87]
	v_mfma_f32_16x16x32_bf16 v[80:83], v[180:183], v[236:239], v[80:83]
	v_mfma_f32_16x16x32_bf16 v[96:99], v[180:183], v[232:235], v[96:99]
	v_mfma_f32_16x16x32_bf16 v[100:103], v[136:139], v[232:235], v[100:103]
	v_mfma_f32_16x16x32_bf16 v[132:135], v[140:143], v[224:227], v[132:135]
	v_mfma_f32_16x16x32_bf16 v[128:131], v[196:199], v[224:227], v[128:131]
	v_mfma_f32_16x16x32_bf16 v[112:115], v[196:199], v[228:231], v[112:115]
	v_mfma_f32_16x16x32_bf16 v[116:119], v[140:143], v[228:231], v[116:119]
	v_mfma_f32_16x16x32_bf16 v[84:87], v[140:143], v[244:247], v[84:87]
	v_mfma_f32_16x16x32_bf16 v[80:83], v[196:199], v[244:247], v[80:83]
	v_mfma_f32_16x16x32_bf16 v[96:99], v[196:199], v[240:243], v[96:99]
	v_mfma_f32_16x16x32_bf16 v[100:103], v[140:143], v[240:243], v[100:103]
	v_mfma_f32_16x16x32_bf16 v[124:127], v[200:203], v[216:219], v[124:127]
	v_mfma_f32_16x16x32_bf16 v[120:123], v[208:211], v[216:219], v[120:123]
	v_mfma_f32_16x16x32_bf16 v[104:107], v[208:211], v[220:223], v[104:107]
	v_mfma_f32_16x16x32_bf16 v[108:111], v[200:203], v[220:223], v[108:111]
	v_mfma_f32_16x16x32_bf16 v[76:79], v[200:203], v[236:239], v[76:79]
	v_mfma_f32_16x16x32_bf16 v[72:75], v[208:211], v[236:239], v[72:75]
	v_mfma_f32_16x16x32_bf16 v[88:91], v[208:211], v[232:235], v[88:91]
	v_mfma_f32_16x16x32_bf16 v[92:95], v[200:203], v[232:235], v[92:95]
	v_mfma_f32_16x16x32_bf16 v[124:127], v[204:207], v[224:227], v[124:127]
	v_mfma_f32_16x16x32_bf16 v[120:123], v[212:215], v[224:227], v[120:123]
	v_mfma_f32_16x16x32_bf16 v[104:107], v[212:215], v[228:231], v[104:107]
	v_mfma_f32_16x16x32_bf16 v[108:111], v[204:207], v[228:231], v[108:111]
	v_mfma_f32_16x16x32_bf16 v[76:79], v[204:207], v[244:247], v[76:79]
	v_mfma_f32_16x16x32_bf16 v[72:75], v[212:215], v[244:247], v[72:75]
	v_mfma_f32_16x16x32_bf16 v[88:91], v[212:215], v[240:243], v[88:91]
	v_mfma_f32_16x16x32_bf16 v[92:95], v[204:207], v[240:243], v[92:95]
	s_barrier
	v_lshl_add_u64 v[184:185], s[34:35], 0, v[146:147]
	s_add_i32 s34, s73, s3
	s_mov_b32 m0, s34
	ds_read_b128 v[216:219], v176 offset:16384
	ds_read_b128 v[220:223], v176 offset:18432
	ds_read_b128 v[224:227], v177 offset:16384
	ds_read_b128 v[228:231], v177 offset:18432
	ds_read_b128 v[232:235], v176 offset:20480
	ds_read_b128 v[236:239], v176 offset:22528
	ds_read_b128 v[240:243], v177 offset:20480
	ds_read_b128 v[244:247], v177 offset:22528
	global_load_lds_dwordx4 v[184:185], off
	v_lshl_add_u64 v[6:7], v[184:185], 0, s[12:13]
	s_add_i32 m0, s34, 0x2000
	s_add_i32 s34, s79, s3
	global_load_lds_dwordx4 v[6:7], off
	v_lshl_add_u64 v[6:7], v[184:185], 0, s[14:15]
	s_mov_b32 m0, s34
	s_nop 0
	global_load_lds_dwordx4 v[6:7], off
	v_lshl_add_u64 v[6:7], v[184:185], 0, s[16:17]
	s_add_i32 m0, s34, 0x2000
	s_nop 0
	global_load_lds_dwordx4 v[6:7], off
	s_waitcnt vmcnt(4)
	s_waitcnt lgkmcnt(0)
	s_barrier
	v_mfma_f32_16x16x32_bf16 v[68:71], v[136:139], v[216:219], v[68:71]
	v_mfma_f32_16x16x32_bf16 v[64:67], v[180:183], v[216:219], v[64:67]
	v_mfma_f32_16x16x32_bf16 v[48:51], v[180:183], v[220:223], v[48:51]
	v_mfma_f32_16x16x32_bf16 v[52:55], v[136:139], v[220:223], v[52:55]
	v_mfma_f32_16x16x32_bf16 v[20:23], v[136:139], v[236:239], v[20:23]
	v_mfma_f32_16x16x32_bf16 v[16:19], v[180:183], v[236:239], v[16:19]
	v_mfma_f32_16x16x32_bf16 v[32:35], v[180:183], v[232:235], v[32:35]
	v_mfma_f32_16x16x32_bf16 v[36:39], v[136:139], v[232:235], v[36:39]
	v_mfma_f32_16x16x32_bf16 v[68:71], v[140:143], v[224:227], v[68:71]
	v_mfma_f32_16x16x32_bf16 v[64:67], v[196:199], v[224:227], v[64:67]
	v_mfma_f32_16x16x32_bf16 v[48:51], v[196:199], v[228:231], v[48:51]
	v_mfma_f32_16x16x32_bf16 v[52:55], v[140:143], v[228:231], v[52:55]
	v_mfma_f32_16x16x32_bf16 v[20:23], v[140:143], v[244:247], v[20:23]
	v_mfma_f32_16x16x32_bf16 v[16:19], v[196:199], v[244:247], v[16:19]
	v_mfma_f32_16x16x32_bf16 v[32:35], v[196:199], v[240:243], v[32:35]
	v_mfma_f32_16x16x32_bf16 v[36:39], v[140:143], v[240:243], v[36:39]
	v_mfma_f32_16x16x32_bf16 v[60:63], v[200:203], v[216:219], v[60:63]
	v_mfma_f32_16x16x32_bf16 v[56:59], v[208:211], v[216:219], v[56:59]
	v_mfma_f32_16x16x32_bf16 v[40:43], v[208:211], v[220:223], v[40:43]
	v_mfma_f32_16x16x32_bf16 v[44:47], v[200:203], v[220:223], v[44:47]
	v_mfma_f32_16x16x32_bf16 v[12:15], v[200:203], v[236:239], v[12:15]
	v_mfma_f32_16x16x32_bf16 v[6:9], v[208:211], v[236:239], v[8:11]
	v_mfma_f32_16x16x32_bf16 v[24:27], v[208:211], v[232:235], v[24:27]
	v_mfma_f32_16x16x32_bf16 v[28:31], v[200:203], v[232:235], v[28:31]
	v_mfma_f32_16x16x32_bf16 v[60:63], v[204:207], v[224:227], v[60:63]
	v_mfma_f32_16x16x32_bf16 v[56:59], v[212:215], v[224:227], v[56:59]
	v_mfma_f32_16x16x32_bf16 v[40:43], v[212:215], v[228:231], v[40:43]
	v_mfma_f32_16x16x32_bf16 v[44:47], v[204:207], v[228:231], v[44:47]
	v_mfma_f32_16x16x32_bf16 v[12:15], v[204:207], v[244:247], v[12:15]
	v_mfma_f32_16x16x32_bf16 v[6:9], v[212:215], v[244:247], v[6:9]
	v_mfma_f32_16x16x32_bf16 v[24:27], v[212:215], v[240:243], v[24:27]
	v_mfma_f32_16x16x32_bf16 v[28:31], v[204:207], v[240:243], v[28:31]
	s_barrier
	v_add_u32_e32 v4, s83, v159
	v_add_u32_e32 v10, s83, v173
	ds_read_b128 v[136:139], v4
	ds_read_b128 v[140:143], v10
	v_add_u32_e32 v4, s81, v159
	v_add_u32_e32 v10, s81, v173
	ds_read_b128 v[180:183], v4
	ds_read_b128 v[196:199], v10
	v_add_u32_e32 v4, s84, v159
	v_add_u32_e32 v10, s84, v173
	ds_read_b128 v[200:203], v4
	ds_read_b128 v[204:207], v10
	v_add_u32_e32 v4, s82, v159
	v_add_u32_e32 v10, s82, v173
	ds_read_b128 v[208:211], v4
	ds_read_b128 v[212:215], v10
	s_mov_b32 m0, s66
	v_lshl_add_u64 v[10:11], s[26:27], 0, v[144:145]
	ds_read_b128 v[216:219], v176 offset:32768
	ds_read_b128 v[220:223], v176 offset:34816
	ds_read_b128 v[224:227], v177 offset:32768
	ds_read_b128 v[228:231], v177 offset:34816
	ds_read_b128 v[232:235], v176 offset:36864
	ds_read_b128 v[236:239], v176 offset:38912
	ds_read_b128 v[240:243], v177 offset:36864
	ds_read_b128 v[244:247], v177 offset:38912
	global_load_lds_dwordx4 v[10:11], off
	v_lshl_add_u64 v[248:249], v[10:11], 0, s[18:19]
	s_mov_b32 m0, s67
	s_nop 0
	global_load_lds_dwordx4 v[248:249], off
	v_lshl_add_u64 v[248:249], v[10:11], 0, s[12:13]
	s_mov_b32 m0, s68
	v_lshl_add_u64 v[10:11], v[10:11], 0, s[20:21]
	global_load_lds_dwordx4 v[248:249], off
	s_mov_b32 m0, s69
	s_nop 0
	global_load_lds_dwordx4 v[10:11], off
	s_waitcnt vmcnt(8)
	s_waitcnt lgkmcnt(0)
	s_barrier
	v_mfma_f32_16x16x32_bf16 v[132:135], v[136:139], v[216:219], v[132:135]
	v_mfma_f32_16x16x32_bf16 v[128:131], v[180:183], v[216:219], v[128:131]
	v_mfma_f32_16x16x32_bf16 v[112:115], v[180:183], v[220:223], v[112:115]
	v_mfma_f32_16x16x32_bf16 v[116:119], v[136:139], v[220:223], v[116:119]
	v_mfma_f32_16x16x32_bf16 v[84:87], v[136:139], v[236:239], v[84:87]
	v_mfma_f32_16x16x32_bf16 v[80:83], v[180:183], v[236:239], v[80:83]
	v_mfma_f32_16x16x32_bf16 v[96:99], v[180:183], v[232:235], v[96:99]
	v_mfma_f32_16x16x32_bf16 v[100:103], v[136:139], v[232:235], v[100:103]
	v_mfma_f32_16x16x32_bf16 v[132:135], v[140:143], v[224:227], v[132:135]
	v_mfma_f32_16x16x32_bf16 v[128:131], v[196:199], v[224:227], v[128:131]
	v_mfma_f32_16x16x32_bf16 v[112:115], v[196:199], v[228:231], v[112:115]
	v_mfma_f32_16x16x32_bf16 v[116:119], v[140:143], v[228:231], v[116:119]
	v_mfma_f32_16x16x32_bf16 v[84:87], v[140:143], v[244:247], v[84:87]
	v_mfma_f32_16x16x32_bf16 v[80:83], v[196:199], v[244:247], v[80:83]
	v_mfma_f32_16x16x32_bf16 v[96:99], v[196:199], v[240:243], v[96:99]
	v_mfma_f32_16x16x32_bf16 v[100:103], v[140:143], v[240:243], v[100:103]
	v_mfma_f32_16x16x32_bf16 v[124:127], v[200:203], v[216:219], v[124:127]
	v_mfma_f32_16x16x32_bf16 v[120:123], v[208:211], v[216:219], v[120:123]
	v_mfma_f32_16x16x32_bf16 v[104:107], v[208:211], v[220:223], v[104:107]
	v_mfma_f32_16x16x32_bf16 v[108:111], v[200:203], v[220:223], v[108:111]
	v_mfma_f32_16x16x32_bf16 v[76:79], v[200:203], v[236:239], v[76:79]
	v_mfma_f32_16x16x32_bf16 v[72:75], v[208:211], v[236:239], v[72:75]
	v_mfma_f32_16x16x32_bf16 v[88:91], v[208:211], v[232:235], v[88:91]
	v_mfma_f32_16x16x32_bf16 v[92:95], v[200:203], v[232:235], v[92:95]
	v_mfma_f32_16x16x32_bf16 v[124:127], v[204:207], v[224:227], v[124:127]
	v_mfma_f32_16x16x32_bf16 v[120:123], v[212:215], v[224:227], v[120:123]
	v_mfma_f32_16x16x32_bf16 v[104:107], v[212:215], v[228:231], v[104:107]
	v_mfma_f32_16x16x32_bf16 v[108:111], v[204:207], v[228:231], v[108:111]
	v_mfma_f32_16x16x32_bf16 v[76:79], v[204:207], v[244:247], v[76:79]
	v_mfma_f32_16x16x32_bf16 v[72:75], v[212:215], v[244:247], v[72:75]
	v_mfma_f32_16x16x32_bf16 v[88:91], v[212:215], v[240:243], v[88:91]
	v_mfma_f32_16x16x32_bf16 v[92:95], v[204:207], v[240:243], v[92:95]
	s_barrier
	s_add_i32 s26, s83, s3
	v_lshl_add_u64 v[10:11], v[184:185], 0, s[24:25]
	s_mov_b32 m0, s26
	ds_read_b128 v[216:219], v176 offset:49152
	ds_read_b128 v[220:223], v176 offset:51200
	ds_read_b128 v[224:227], v177 offset:49152
	ds_read_b128 v[228:231], v177 offset:51200
	ds_read_b128 v[232:235], v176 offset:53248
	ds_read_b128 v[236:239], v176 offset:55296
	ds_read_b128 v[240:243], v177 offset:53248
	ds_read_b128 v[244:247], v177 offset:55296
	global_load_lds_dwordx4 v[10:11], off
	v_lshl_add_u64 v[10:11], v[184:185], 0, s[50:51]
	s_add_i32 m0, s26, 0x2000
	s_add_i32 s26, s84, s3
	global_load_lds_dwordx4 v[10:11], off
	v_lshl_add_u64 v[10:11], v[184:185], 0, s[52:53]
	s_mov_b32 m0, s26
	s_nop 0
	global_load_lds_dwordx4 v[10:11], off
	v_lshl_add_u64 v[10:11], v[184:185], 0, s[54:55]
	s_add_i32 m0, s26, 0x2000
	s_nop 0
	global_load_lds_dwordx4 v[10:11], off
	s_waitcnt vmcnt(4)
	s_waitcnt lgkmcnt(0)
	s_barrier
	v_mfma_f32_16x16x32_bf16 v[68:71], v[136:139], v[216:219], v[68:71]
	v_mfma_f32_16x16x32_bf16 v[64:67], v[180:183], v[216:219], v[64:67]
	v_mfma_f32_16x16x32_bf16 v[48:51], v[180:183], v[220:223], v[48:51]
	v_mfma_f32_16x16x32_bf16 v[52:55], v[136:139], v[220:223], v[52:55]
	v_mfma_f32_16x16x32_bf16 v[20:23], v[136:139], v[236:239], v[20:23]
	v_mfma_f32_16x16x32_bf16 v[16:19], v[180:183], v[236:239], v[16:19]
	v_mfma_f32_16x16x32_bf16 v[32:35], v[180:183], v[232:235], v[32:35]
	v_mfma_f32_16x16x32_bf16 v[36:39], v[136:139], v[232:235], v[36:39]
	v_mfma_f32_16x16x32_bf16 v[68:71], v[140:143], v[224:227], v[68:71]
	v_mfma_f32_16x16x32_bf16 v[64:67], v[196:199], v[224:227], v[64:67]
	v_mfma_f32_16x16x32_bf16 v[48:51], v[196:199], v[228:231], v[48:51]
	v_mfma_f32_16x16x32_bf16 v[52:55], v[140:143], v[228:231], v[52:55]
	v_mfma_f32_16x16x32_bf16 v[20:23], v[140:143], v[244:247], v[20:23]
	v_mfma_f32_16x16x32_bf16 v[16:19], v[196:199], v[244:247], v[16:19]
	v_mfma_f32_16x16x32_bf16 v[32:35], v[196:199], v[240:243], v[32:35]
	v_mfma_f32_16x16x32_bf16 v[36:39], v[140:143], v[240:243], v[36:39]
	v_mfma_f32_16x16x32_bf16 v[60:63], v[200:203], v[216:219], v[60:63]
	v_mfma_f32_16x16x32_bf16 v[56:59], v[208:211], v[216:219], v[56:59]
	v_mfma_f32_16x16x32_bf16 v[40:43], v[208:211], v[220:223], v[40:43]
	v_mfma_f32_16x16x32_bf16 v[44:47], v[200:203], v[220:223], v[44:47]
	v_mfma_f32_16x16x32_bf16 v[10:13], v[200:203], v[236:239], v[12:15]
	v_mfma_f32_16x16x32_bf16 v[6:9], v[208:211], v[236:239], v[6:9]
	v_mfma_f32_16x16x32_bf16 v[24:27], v[208:211], v[232:235], v[24:27]
	v_mfma_f32_16x16x32_bf16 v[28:31], v[200:203], v[232:235], v[28:31]
	v_mfma_f32_16x16x32_bf16 v[60:63], v[204:207], v[224:227], v[60:63]
	v_mfma_f32_16x16x32_bf16 v[56:59], v[212:215], v[224:227], v[56:59]
	v_mfma_f32_16x16x32_bf16 v[40:43], v[212:215], v[228:231], v[40:43]
	v_mfma_f32_16x16x32_bf16 v[44:47], v[204:207], v[228:231], v[44:47]
	v_mfma_f32_16x16x32_bf16 v[12:15], v[204:207], v[244:247], v[10:13]
	v_mfma_f32_16x16x32_bf16 v[8:11], v[212:215], v[244:247], v[6:9]
	v_mfma_f32_16x16x32_bf16 v[24:27], v[212:215], v[240:243], v[24:27]
	v_mfma_f32_16x16x32_bf16 v[28:31], v[204:207], v[240:243], v[28:31]
	s_barrier
	s_add_i32 s95, s95, 2
	s_add_u32 s64, s64, 0x100
	s_addc_u32 s65, s65, 0
	s_cmp_gt_u32 s95, 21
	s_cbranch_scc1 .LBB0_782

.LBB0_973:
	v_add_u32_e32 v133, s72, v163
	v_add_u32_e32 v140, s72, v164
	ds_read_b128 v[136:139], v133
	ds_read_b128 v[148:151], v140
	v_add_u32_e32 v133, s73, v163
	s_add_u32 s70, s28, s26
	v_add_u32_e32 v140, s73, v164
	s_waitcnt lgkmcnt(0)
	ds_read_b128 v[152:155], v133
	ds_read_b128 v[174:177], v140
	v_add_u32_e32 v133, s77, v163
	s_addc_u32 s71, s29, s27
	v_add_u32_e32 v140, s77, v164
	ds_read_b128 v[178:181], v133
	ds_read_b128 v[182:185], v140
	v_add_u32_e32 v133, s79, v163
	s_add_u32 s70, s70, 0x100
	v_add_u32_e32 v140, s79, v164
	ds_read_b128 v[196:199], v133
	ds_read_b128 v[200:203], v140
	s_addc_u32 s71, s71, 0
	s_add_u32 s86, s65, s26
	s_addc_u32 s87, s85, s27
	s_cmpk_eq_i32 s26, 0x700
	s_cselect_b32 s87, s61, s87
	s_cselect_b32 s86, s88, s86
	s_cselect_b32 s71, s54, s71
	s_cselect_b32 s70, s63, s70
	v_lshl_add_u64 v[140:141], v[134:135], 0, s[26:27]
	v_lshl_add_u64 v[160:161], v[140:141], 0, s[36:37]
	s_add_i32 m0, s5, 0x8000
	s_mov_b64 s[90:91], 0x20080
	ds_read_b128 v[204:207], v166
	ds_read_b128 v[208:211], v166 offset:2048
	ds_read_b128 v[212:215], v167
	ds_read_b128 v[216:219], v167 offset:2048
	ds_read_b128 v[220:223], v166 offset:4096
	ds_read_b128 v[224:227], v166 offset:6144
	ds_read_b128 v[228:231], v167 offset:4096
	ds_read_b128 v[232:235], v167 offset:6144
	global_load_lds_dwordx4 v[160:161], off
	v_lshl_add_u64 v[160:161], v[140:141], 0, s[90:91]
	s_add_i32 m0, s5, 0xa000
	s_mov_b64 s[90:91], 0x60080
	global_load_lds_dwordx4 v[160:161], off
	v_lshl_add_u64 v[160:161], v[140:141], 0, s[44:45]
	s_add_i32 m0, s5, 0xc000
	v_lshl_add_u64 v[140:141], v[140:141], 0, s[90:91]
	global_load_lds_dwordx4 v[160:161], off
	s_add_i32 m0, s5, 0xe000
	s_nop 0
	global_load_lds_dwordx4 v[140:141], off
	s_waitcnt vmcnt(8)
	s_waitcnt lgkmcnt(0)
	s_barrier
	v_mfma_f32_16x16x32_bf16 v[8:11], v[136:139], v[204:207], v[8:11]
	v_mfma_f32_16x16x32_bf16 v[4:7], v[152:155], v[204:207], v[4:7]
	v_mfma_f32_16x16x32_bf16 v[16:19], v[152:155], v[208:211], v[16:19]
	v_mfma_f32_16x16x32_bf16 v[12:15], v[136:139], v[208:211], v[12:15]
	v_mfma_f32_16x16x32_bf16 v[20:23], v[136:139], v[224:227], v[20:23]
	v_mfma_f32_16x16x32_bf16 v[24:27], v[152:155], v[224:227], v[24:27]
	v_mfma_f32_16x16x32_bf16 v[36:39], v[152:155], v[220:223], v[36:39]
	v_mfma_f32_16x16x32_bf16 v[44:47], v[136:139], v[220:223], v[44:47]
	v_mfma_f32_16x16x32_bf16 v[8:11], v[148:151], v[212:215], v[8:11]
	v_mfma_f32_16x16x32_bf16 v[4:7], v[174:177], v[212:215], v[4:7]
	v_mfma_f32_16x16x32_bf16 v[16:19], v[174:177], v[216:219], v[16:19]
	v_mfma_f32_16x16x32_bf16 v[12:15], v[148:151], v[216:219], v[12:15]
	v_mfma_f32_16x16x32_bf16 v[20:23], v[148:151], v[232:235], v[20:23]
	v_mfma_f32_16x16x32_bf16 v[24:27], v[174:177], v[232:235], v[24:27]
	v_mfma_f32_16x16x32_bf16 v[36:39], v[174:177], v[228:231], v[36:39]
	v_mfma_f32_16x16x32_bf16 v[44:47], v[148:151], v[228:231], v[44:47]
	v_mfma_f32_16x16x32_bf16 v[32:35], v[178:181], v[204:207], v[32:35]
	v_mfma_f32_16x16x32_bf16 v[28:31], v[196:199], v[204:207], v[28:31]
	v_mfma_f32_16x16x32_bf16 v[52:55], v[196:199], v[208:211], v[52:55]
	v_mfma_f32_16x16x32_bf16 v[40:43], v[178:181], v[208:211], v[40:43]
	v_mfma_f32_16x16x32_bf16 v[56:59], v[178:181], v[224:227], v[56:59]
	v_mfma_f32_16x16x32_bf16 v[64:67], v[196:199], v[224:227], v[64:67]
	v_mfma_f32_16x16x32_bf16 v[60:63], v[196:199], v[220:223], v[60:63]
	v_mfma_f32_16x16x32_bf16 v[48:51], v[178:181], v[220:223], v[48:51]
	v_mfma_f32_16x16x32_bf16 v[32:35], v[182:185], v[212:215], v[32:35]
	v_mfma_f32_16x16x32_bf16 v[28:31], v[200:203], v[212:215], v[28:31]
	v_mfma_f32_16x16x32_bf16 v[52:55], v[200:203], v[216:219], v[52:55]
	v_mfma_f32_16x16x32_bf16 v[40:43], v[182:185], v[216:219], v[40:43]
	v_mfma_f32_16x16x32_bf16 v[56:59], v[182:185], v[232:235], v[56:59]
	v_mfma_f32_16x16x32_bf16 v[64:67], v[200:203], v[232:235], v[64:67]
	v_mfma_f32_16x16x32_bf16 v[60:63], v[200:203], v[228:231], v[60:63]
	v_mfma_f32_16x16x32_bf16 v[48:51], v[182:185], v[228:231], v[48:51]
	s_barrier
	v_lshl_add_u64 v[140:141], s[86:87], 0, v[158:159]
	s_add_i32 s86, s72, s34
	s_mov_b32 m0, s86
	ds_read_b128 v[204:207], v166 offset:16384
	ds_read_b128 v[208:211], v166 offset:18432
	ds_read_b128 v[212:215], v167 offset:16384
	ds_read_b128 v[216:219], v167 offset:18432
	ds_read_b128 v[220:223], v166 offset:20480
	ds_read_b128 v[224:227], v166 offset:22528
	ds_read_b128 v[228:231], v167 offset:20480
	ds_read_b128 v[232:235], v167 offset:22528
	global_load_lds_dwordx4 v[140:141], off
	v_lshl_add_u64 v[160:161], v[140:141], 0, s[18:19]
	s_add_i32 m0, s86, 0x2000
	s_mov_b64 s[86:87], 0x10000
	global_load_lds_dwordx4 v[160:161], off
	v_lshl_add_u64 v[160:161], v[140:141], 0, s[86:87]
	s_add_i32 s86, s77, s34
	s_mov_b32 m0, s86
	s_nop 0
	global_load_lds_dwordx4 v[160:161], off
	v_lshl_add_u64 v[160:161], v[140:141], 0, s[20:21]
	s_add_i32 m0, s86, 0x2000
	s_nop 0
	global_load_lds_dwordx4 v[160:161], off
	s_waitcnt vmcnt(4)
	s_waitcnt lgkmcnt(0)
	s_barrier
	v_mfma_f32_16x16x32_bf16 v[68:71], v[136:139], v[204:207], v[68:71]
	v_mfma_f32_16x16x32_bf16 v[72:75], v[152:155], v[204:207], v[72:75]
	v_mfma_f32_16x16x32_bf16 v[84:87], v[152:155], v[208:211], v[84:87]
	v_mfma_f32_16x16x32_bf16 v[92:95], v[136:139], v[208:211], v[92:95]
	v_mfma_f32_16x16x32_bf16 v[116:119], v[136:139], v[224:227], v[116:119]
	v_mfma_f32_16x16x32_bf16 v[108:111], v[152:155], v[224:227], v[108:111]
	v_mfma_f32_16x16x32_bf16 v[80:83], v[152:155], v[220:223], v[80:83]
	v_mfma_f32_16x16x32_bf16 v[76:79], v[136:139], v[220:223], v[76:79]
	v_mfma_f32_16x16x32_bf16 v[68:71], v[148:151], v[212:215], v[68:71]
	v_mfma_f32_16x16x32_bf16 v[72:75], v[174:177], v[212:215], v[72:75]
	v_mfma_f32_16x16x32_bf16 v[84:87], v[174:177], v[216:219], v[84:87]
	v_mfma_f32_16x16x32_bf16 v[92:95], v[148:151], v[216:219], v[92:95]
	v_mfma_f32_16x16x32_bf16 v[116:119], v[148:151], v[232:235], v[116:119]
	v_mfma_f32_16x16x32_bf16 v[108:111], v[174:177], v[232:235], v[108:111]
	v_mfma_f32_16x16x32_bf16 v[80:83], v[174:177], v[228:231], v[80:83]
	v_mfma_f32_16x16x32_bf16 v[76:79], v[148:151], v[228:231], v[76:79]
	v_mfma_f32_16x16x32_bf16 v[88:91], v[178:181], v[204:207], v[88:91]
	v_mfma_f32_16x16x32_bf16 v[100:103], v[196:199], v[204:207], v[100:103]
	v_mfma_f32_16x16x32_bf16 v[104:107], v[196:199], v[208:211], v[104:107]
	v_mfma_f32_16x16x32_bf16 v[96:99], v[178:181], v[208:211], v[96:99]
	v_mfma_f32_16x16x32_bf16 v[120:123], v[178:181], v[224:227], v[120:123]
	v_mfma_f32_16x16x32_bf16 v[128:131], v[196:199], v[224:227], v[128:131]
	v_mfma_f32_16x16x32_bf16 v[124:127], v[196:199], v[220:223], v[124:127]
	v_mfma_f32_16x16x32_bf16 v[112:115], v[178:181], v[220:223], v[112:115]
	v_mfma_f32_16x16x32_bf16 v[88:91], v[182:185], v[212:215], v[88:91]
	v_mfma_f32_16x16x32_bf16 v[100:103], v[200:203], v[212:215], v[100:103]
	v_mfma_f32_16x16x32_bf16 v[104:107], v[200:203], v[216:219], v[104:107]
	v_mfma_f32_16x16x32_bf16 v[96:99], v[182:185], v[216:219], v[96:99]
	v_mfma_f32_16x16x32_bf16 v[120:123], v[182:185], v[232:235], v[120:123]
	v_mfma_f32_16x16x32_bf16 v[128:131], v[200:203], v[232:235], v[128:131]
	v_mfma_f32_16x16x32_bf16 v[124:127], v[200:203], v[228:231], v[124:127]
	v_mfma_f32_16x16x32_bf16 v[112:115], v[182:185], v[228:231], v[112:115]
	s_barrier
	v_add_u32_e32 v133, s82, v163
	v_add_u32_e32 v148, s82, v164
	ds_read_b128 v[136:139], v133
	ds_read_b128 v[148:151], v148
	v_add_u32_e32 v133, s80, v163
	v_add_u32_e32 v160, s80, v164
	ds_read_b128 v[152:155], v133
	ds_read_b128 v[174:177], v160
	v_add_u32_e32 v133, s83, v163
	v_add_u32_e32 v160, s83, v164
	ds_read_b128 v[178:181], v133
	ds_read_b128 v[182:185], v160
	v_add_u32_e32 v133, s81, v163
	v_add_u32_e32 v160, s81, v164
	ds_read_b128 v[196:199], v133
	ds_read_b128 v[200:203], v160
	s_mov_b32 m0, s5
	v_lshl_add_u64 v[160:161], s[70:71], 0, v[0:1]
	s_mov_b64 s[70:71], 0x20000
	ds_read_b128 v[204:207], v166 offset:32768
	ds_read_b128 v[208:211], v166 offset:34816
	ds_read_b128 v[212:215], v167 offset:32768
	ds_read_b128 v[216:219], v167 offset:34816
	ds_read_b128 v[220:223], v166 offset:36864
	ds_read_b128 v[224:227], v166 offset:38912
	ds_read_b128 v[228:231], v167 offset:36864
	ds_read_b128 v[232:235], v167 offset:38912
	global_load_lds_dwordx4 v[160:161], off
	v_lshl_add_u64 v[170:171], v[160:161], 0, s[70:71]
	s_mov_b32 m0, s17
	s_nop 0
	global_load_lds_dwordx4 v[170:171], off
	v_lshl_add_u64 v[170:171], v[160:161], 0, s[18:19]
	s_mov_b32 m0, s35
	v_lshl_add_u64 v[160:161], v[160:161], 0, s[22:23]
	global_load_lds_dwordx4 v[170:171], off
	s_mov_b32 m0, s38
	s_nop 0
	global_load_lds_dwordx4 v[160:161], off
	s_waitcnt vmcnt(8)
	s_waitcnt lgkmcnt(0)
	s_barrier
	v_mfma_f32_16x16x32_bf16 v[8:11], v[136:139], v[204:207], v[8:11]
	v_mfma_f32_16x16x32_bf16 v[4:7], v[152:155], v[204:207], v[4:7]
	v_mfma_f32_16x16x32_bf16 v[16:19], v[152:155], v[208:211], v[16:19]
	v_mfma_f32_16x16x32_bf16 v[12:15], v[136:139], v[208:211], v[12:15]
	v_mfma_f32_16x16x32_bf16 v[20:23], v[136:139], v[224:227], v[20:23]
	v_mfma_f32_16x16x32_bf16 v[24:27], v[152:155], v[224:227], v[24:27]
	v_mfma_f32_16x16x32_bf16 v[36:39], v[152:155], v[220:223], v[36:39]
	v_mfma_f32_16x16x32_bf16 v[44:47], v[136:139], v[220:223], v[44:47]
	v_mfma_f32_16x16x32_bf16 v[8:11], v[148:151], v[212:215], v[8:11]
	v_mfma_f32_16x16x32_bf16 v[4:7], v[174:177], v[212:215], v[4:7]
	v_mfma_f32_16x16x32_bf16 v[16:19], v[174:177], v[216:219], v[16:19]
	v_mfma_f32_16x16x32_bf16 v[12:15], v[148:151], v[216:219], v[12:15]
	v_mfma_f32_16x16x32_bf16 v[20:23], v[148:151], v[232:235], v[20:23]
	v_mfma_f32_16x16x32_bf16 v[24:27], v[174:177], v[232:235], v[24:27]
	v_mfma_f32_16x16x32_bf16 v[36:39], v[174:177], v[228:231], v[36:39]
	v_mfma_f32_16x16x32_bf16 v[44:47], v[148:151], v[228:231], v[44:47]
	v_mfma_f32_16x16x32_bf16 v[32:35], v[178:181], v[204:207], v[32:35]
	v_mfma_f32_16x16x32_bf16 v[28:31], v[196:199], v[204:207], v[28:31]
	v_mfma_f32_16x16x32_bf16 v[52:55], v[196:199], v[208:211], v[52:55]
	v_mfma_f32_16x16x32_bf16 v[40:43], v[178:181], v[208:211], v[40:43]
	v_mfma_f32_16x16x32_bf16 v[56:59], v[178:181], v[224:227], v[56:59]
	v_mfma_f32_16x16x32_bf16 v[64:67], v[196:199], v[224:227], v[64:67]
	v_mfma_f32_16x16x32_bf16 v[60:63], v[196:199], v[220:223], v[60:63]
	v_mfma_f32_16x16x32_bf16 v[48:51], v[178:181], v[220:223], v[48:51]
	v_mfma_f32_16x16x32_bf16 v[32:35], v[182:185], v[212:215], v[32:35]
	v_mfma_f32_16x16x32_bf16 v[28:31], v[200:203], v[212:215], v[28:31]
	v_mfma_f32_16x16x32_bf16 v[52:55], v[200:203], v[216:219], v[52:55]
	v_mfma_f32_16x16x32_bf16 v[40:43], v[182:185], v[216:219], v[40:43]
	v_mfma_f32_16x16x32_bf16 v[56:59], v[182:185], v[232:235], v[56:59]
	v_mfma_f32_16x16x32_bf16 v[64:67], v[200:203], v[232:235], v[64:67]
	v_mfma_f32_16x16x32_bf16 v[60:63], v[200:203], v[228:231], v[60:63]
	v_mfma_f32_16x16x32_bf16 v[48:51], v[182:185], v[228:231], v[48:51]
	s_barrier
	s_add_i32 s70, s82, s34
	v_lshl_add_u64 v[160:161], v[140:141], 0, s[36:37]
	s_mov_b32 m0, s70
	ds_read_b128 v[204:207], v166 offset:49152
	ds_read_b128 v[208:211], v166 offset:51200
	ds_read_b128 v[212:215], v167 offset:49152
	ds_read_b128 v[216:219], v167 offset:51200
	ds_read_b128 v[220:223], v166 offset:53248
	ds_read_b128 v[224:227], v166 offset:55296
	ds_read_b128 v[228:231], v167 offset:53248
	ds_read_b128 v[232:235], v167 offset:55296
	global_load_lds_dwordx4 v[160:161], off
	v_lshl_add_u64 v[160:161], v[140:141], 0, s[44:45]
	s_add_i32 m0, s70, 0x2000
	s_add_i32 s70, s83, s34
	global_load_lds_dwordx4 v[160:161], off
	v_lshl_add_u64 v[160:161], v[140:141], 0, s[46:47]
	s_mov_b32 m0, s70
	v_lshl_add_u64 v[140:141], v[140:141], 0, s[50:51]
	global_load_lds_dwordx4 v[160:161], off
	s_add_i32 m0, s70, 0x2000
	s_nop 0
	global_load_lds_dwordx4 v[140:141], off
	s_waitcnt vmcnt(4)
	s_waitcnt lgkmcnt(0)
	s_barrier
	v_mfma_f32_16x16x32_bf16 v[68:71], v[136:139], v[204:207], v[68:71]
	v_mfma_f32_16x16x32_bf16 v[72:75], v[152:155], v[204:207], v[72:75]
	v_mfma_f32_16x16x32_bf16 v[84:87], v[152:155], v[208:211], v[84:87]
	v_mfma_f32_16x16x32_bf16 v[92:95], v[136:139], v[208:211], v[92:95]
	v_mfma_f32_16x16x32_bf16 v[116:119], v[136:139], v[224:227], v[116:119]
	v_mfma_f32_16x16x32_bf16 v[108:111], v[152:155], v[224:227], v[108:111]
	v_mfma_f32_16x16x32_bf16 v[80:83], v[152:155], v[220:223], v[80:83]
	v_mfma_f32_16x16x32_bf16 v[76:79], v[136:139], v[220:223], v[76:79]
	v_mfma_f32_16x16x32_bf16 v[68:71], v[148:151], v[212:215], v[68:71]
	v_mfma_f32_16x16x32_bf16 v[72:75], v[174:177], v[212:215], v[72:75]
	v_mfma_f32_16x16x32_bf16 v[84:87], v[174:177], v[216:219], v[84:87]
	v_mfma_f32_16x16x32_bf16 v[92:95], v[148:151], v[216:219], v[92:95]
	v_mfma_f32_16x16x32_bf16 v[116:119], v[148:151], v[232:235], v[116:119]
	v_mfma_f32_16x16x32_bf16 v[108:111], v[174:177], v[232:235], v[108:111]
	v_mfma_f32_16x16x32_bf16 v[80:83], v[174:177], v[228:231], v[80:83]
	v_mfma_f32_16x16x32_bf16 v[76:79], v[148:151], v[228:231], v[76:79]
	v_mfma_f32_16x16x32_bf16 v[88:91], v[178:181], v[204:207], v[88:91]
	v_mfma_f32_16x16x32_bf16 v[100:103], v[196:199], v[204:207], v[100:103]
	v_mfma_f32_16x16x32_bf16 v[104:107], v[196:199], v[208:211], v[104:107]
	v_mfma_f32_16x16x32_bf16 v[96:99], v[178:181], v[208:211], v[96:99]
	v_mfma_f32_16x16x32_bf16 v[120:123], v[178:181], v[224:227], v[120:123]
	v_mfma_f32_16x16x32_bf16 v[128:131], v[196:199], v[224:227], v[128:131]
	v_mfma_f32_16x16x32_bf16 v[124:127], v[196:199], v[220:223], v[124:127]
	v_mfma_f32_16x16x32_bf16 v[112:115], v[178:181], v[220:223], v[112:115]
	v_mfma_f32_16x16x32_bf16 v[88:91], v[182:185], v[212:215], v[88:91]
	v_mfma_f32_16x16x32_bf16 v[100:103], v[200:203], v[212:215], v[100:103]
	v_mfma_f32_16x16x32_bf16 v[104:107], v[200:203], v[216:219], v[104:107]
	v_mfma_f32_16x16x32_bf16 v[96:99], v[182:185], v[216:219], v[96:99]
	v_mfma_f32_16x16x32_bf16 v[120:123], v[182:185], v[232:235], v[120:123]
	v_mfma_f32_16x16x32_bf16 v[128:131], v[200:203], v[232:235], v[128:131]
	v_mfma_f32_16x16x32_bf16 v[124:127], v[200:203], v[228:231], v[124:127]
	v_mfma_f32_16x16x32_bf16 v[112:115], v[182:185], v[228:231], v[112:115]
	s_barrier
	s_add_i32 s89, s89, 2
	s_add_u32 s26, s26, 0x100
	s_addc_u32 s27, s27, 0
	s_cmp_gt_u32 s89, 13
	s_cbranch_scc0 .LBB0_973
	s_and_b64 vcc, exec, s[52:53]
	s_cbranch_vccz .LBB0_976
	s_barrier

.LBB0_1134:
	s_ashr_i32 s57, s56, 31
	s_lshl_b64 s[60:61], s[56:57], 19
	s_add_u32 s60, s42, s60
	s_addc_u32 s61, s43, s61
	s_and_b64 s[62:63], s[10:11], exec
	s_cselect_b32 s57, s61, s27
	s_cselect_b32 s79, s60, s26
	s_ashr_i32 s59, s58, 31
	s_lshl_b64 s[62:63], s[58:59], 19
	v_readlane_b32 s70, v254, 7
	v_readlane_b32 s71, v254, 8
	s_add_u32 s62, s70, s62
	s_addc_u32 s63, s71, s63
	s_and_b64 s[70:71], s[10:11], exec
	s_cselect_b32 s59, s63, s69
	s_cselect_b32 s80, s62, s68
	s_add_u32 s81, s68, 0x100
	v_lshl_add_u64 v[138:139], s[26:27], 0, v[132:133]
	s_addc_u32 s82, s69, 0
	s_mov_b32 s83, -2
	s_mov_b64 s[68:69], 0
	ds_read_b128 v[168:171], v145
	ds_read_b128 v[174:177], v146
	ds_read_b128 v[178:181], v147
	ds_read_b128 v[182:185], v148
	ds_read_b128 v[194:197], v149
	ds_read_b128 v[198:201], v150
	ds_read_b128 v[202:205], v151
	ds_read_b128 v[206:209], v152
	s_add_u32 s70, s26, s68
	s_addc_u32 s71, s27, s69
	s_add_u32 s70, s70, 0x100
	s_addc_u32 s71, s71, 0
	s_add_u32 s84, s81, s68
	s_addc_u32 s85, s82, s69
	s_cmpk_eq_i32 s68, 0x700
	s_cselect_b32 s85, s59, s85
	s_cselect_b32 s84, s80, s84
	s_cselect_b32 s71, s57, s71
	s_cselect_b32 s70, s79, s70
	v_lshl_add_u64 v[140:141], v[138:139], 0, s[68:69]
	v_lshl_add_u64 v[242:243], v[140:141], 0, s[22:23]
	s_add_i32 m0, s34, 0x8000
	s_mov_b64 s[86:87], 0x20080
	ds_read_b128 v[210:213], v153
	ds_read_b128 v[214:217], v153 offset:2048
	ds_read_b128 v[218:221], v154
	ds_read_b128 v[222:225], v154 offset:2048
	ds_read_b128 v[226:229], v153 offset:4096
	ds_read_b128 v[230:233], v153 offset:6144
	ds_read_b128 v[234:237], v154 offset:4096
	ds_read_b128 v[238:241], v154 offset:6144
	global_load_lds_dwordx4 v[242:243], off
	v_lshl_add_u64 v[242:243], v[140:141], 0, s[86:87]
	s_add_i32 m0, s34, 0xa000
	s_mov_b64 s[86:87], 0x60080
	global_load_lds_dwordx4 v[242:243], off
	v_lshl_add_u64 v[242:243], v[140:141], 0, s[24:25]
	s_add_i32 m0, s34, 0xc000
	v_lshl_add_u64 v[140:141], v[140:141], 0, s[86:87]
	global_load_lds_dwordx4 v[242:243], off
	s_add_i32 m0, s34, 0xe000
	s_nop 0
	global_load_lds_dwordx4 v[140:141], off
	s_waitcnt lgkmcnt(0)
	s_barrier
	v_mfma_f32_16x16x32_bf16 v[128:131], v[168:171], v[210:213], 0
	v_mfma_f32_16x16x32_bf16 v[124:127], v[178:181], v[210:213], 0
	v_mfma_f32_16x16x32_bf16 v[108:111], v[178:181], v[214:217], 0
	v_mfma_f32_16x16x32_bf16 v[112:115], v[168:171], v[214:217], 0
	v_mfma_f32_16x16x32_bf16 v[80:83], v[168:171], v[230:233], 0
	v_mfma_f32_16x16x32_bf16 v[76:79], v[178:181], v[230:233], 0
	v_mfma_f32_16x16x32_bf16 v[92:95], v[178:181], v[226:229], 0
	v_mfma_f32_16x16x32_bf16 v[96:99], v[168:171], v[226:229], 0
	v_mfma_f32_16x16x32_bf16 v[128:131], v[174:177], v[218:221], v[128:131]
	v_mfma_f32_16x16x32_bf16 v[124:127], v[182:185], v[218:221], v[124:127]
	v_mfma_f32_16x16x32_bf16 v[108:111], v[182:185], v[222:225], v[108:111]
	v_mfma_f32_16x16x32_bf16 v[112:115], v[174:177], v[222:225], v[112:115]
	v_mfma_f32_16x16x32_bf16 v[80:83], v[174:177], v[238:241], v[80:83]
	v_mfma_f32_16x16x32_bf16 v[76:79], v[182:185], v[238:241], v[76:79]
	v_mfma_f32_16x16x32_bf16 v[92:95], v[182:185], v[234:237], v[92:95]
	v_mfma_f32_16x16x32_bf16 v[96:99], v[174:177], v[234:237], v[96:99]
	v_mfma_f32_16x16x32_bf16 v[120:123], v[194:197], v[210:213], 0
	v_mfma_f32_16x16x32_bf16 v[116:119], v[202:205], v[210:213], 0
	v_mfma_f32_16x16x32_bf16 v[100:103], v[202:205], v[214:217], 0
	v_mfma_f32_16x16x32_bf16 v[104:107], v[194:197], v[214:217], 0
	v_mfma_f32_16x16x32_bf16 v[72:75], v[194:197], v[230:233], 0
	v_mfma_f32_16x16x32_bf16 v[68:71], v[202:205], v[230:233], 0
	v_mfma_f32_16x16x32_bf16 v[84:87], v[202:205], v[226:229], 0
	v_mfma_f32_16x16x32_bf16 v[88:91], v[194:197], v[226:229], 0
	v_mfma_f32_16x16x32_bf16 v[120:123], v[198:201], v[218:221], v[120:123]
	v_mfma_f32_16x16x32_bf16 v[116:119], v[206:209], v[218:221], v[116:119]
	v_mfma_f32_16x16x32_bf16 v[100:103], v[206:209], v[222:225], v[100:103]
	v_mfma_f32_16x16x32_bf16 v[104:107], v[198:201], v[222:225], v[104:107]
	v_mfma_f32_16x16x32_bf16 v[72:75], v[198:201], v[238:241], v[72:75]
	v_mfma_f32_16x16x32_bf16 v[68:71], v[206:209], v[238:241], v[68:71]
	v_mfma_f32_16x16x32_bf16 v[84:87], v[206:209], v[234:237], v[84:87]
	v_mfma_f32_16x16x32_bf16 v[88:91], v[198:201], v[234:237], v[88:91]
	s_barrier
	v_lshl_add_u64 v[140:141], s[84:85], 0, v[158:159]
	s_add_i32 s84, s67, s3
	s_mov_b32 m0, s84
	ds_read_b128 v[210:213], v153 offset:16384
	ds_read_b128 v[214:217], v153 offset:18432
	ds_read_b128 v[218:221], v154 offset:16384
	ds_read_b128 v[222:225], v154 offset:18432
	ds_read_b128 v[226:229], v153 offset:20480
	ds_read_b128 v[230:233], v153 offset:22528
	ds_read_b128 v[234:237], v154 offset:20480
	ds_read_b128 v[238:241], v154 offset:22528
	global_load_lds_dwordx4 v[140:141], off
	v_lshl_add_u64 v[242:243], v[140:141], 0, s[0:1]
	s_add_i32 m0, s84, 0x2000
	s_add_i32 s84, s72, s3
	global_load_lds_dwordx4 v[242:243], off
	v_lshl_add_u64 v[242:243], v[140:141], 0, s[12:13]
	s_mov_b32 m0, s84
	s_nop 0
	global_load_lds_dwordx4 v[242:243], off
	v_lshl_add_u64 v[242:243], v[140:141], 0, s[14:15]
	s_add_i32 m0, s84, 0x2000
	s_nop 0
	global_load_lds_dwordx4 v[242:243], off
	s_waitcnt vmcnt(4)
	s_waitcnt lgkmcnt(0)
	s_barrier
	v_mfma_f32_16x16x32_bf16 v[64:67], v[168:171], v[210:213], 0
	v_mfma_f32_16x16x32_bf16 v[60:63], v[178:181], v[210:213], 0
	v_mfma_f32_16x16x32_bf16 v[44:47], v[178:181], v[214:217], 0
	v_mfma_f32_16x16x32_bf16 v[48:51], v[168:171], v[214:217], 0
	v_mfma_f32_16x16x32_bf16 v[16:19], v[168:171], v[230:233], 0
	v_mfma_f32_16x16x32_bf16 v[12:15], v[178:181], v[230:233], 0
	v_mfma_f32_16x16x32_bf16 v[28:31], v[178:181], v[226:229], 0
	v_mfma_f32_16x16x32_bf16 v[32:35], v[168:171], v[226:229], 0
	v_mfma_f32_16x16x32_bf16 v[64:67], v[174:177], v[218:221], v[64:67]
	v_mfma_f32_16x16x32_bf16 v[60:63], v[182:185], v[218:221], v[60:63]
	v_mfma_f32_16x16x32_bf16 v[44:47], v[182:185], v[222:225], v[44:47]
	v_mfma_f32_16x16x32_bf16 v[48:51], v[174:177], v[222:225], v[48:51]
	v_mfma_f32_16x16x32_bf16 v[16:19], v[174:177], v[238:241], v[16:19]
	v_mfma_f32_16x16x32_bf16 v[12:15], v[182:185], v[238:241], v[12:15]
	v_mfma_f32_16x16x32_bf16 v[28:31], v[182:185], v[234:237], v[28:31]
	v_mfma_f32_16x16x32_bf16 v[32:35], v[174:177], v[234:237], v[32:35]
	v_mfma_f32_16x16x32_bf16 v[56:59], v[194:197], v[210:213], 0
	v_mfma_f32_16x16x32_bf16 v[52:55], v[202:205], v[210:213], 0
	v_mfma_f32_16x16x32_bf16 v[36:39], v[202:205], v[214:217], 0
	v_mfma_f32_16x16x32_bf16 v[40:43], v[194:197], v[214:217], 0
	v_mfma_f32_16x16x32_bf16 v[8:11], v[194:197], v[230:233], 0
	v_mfma_f32_16x16x32_bf16 v[4:7], v[202:205], v[230:233], 0
	v_mfma_f32_16x16x32_bf16 v[20:23], v[202:205], v[226:229], 0
	v_mfma_f32_16x16x32_bf16 v[24:27], v[194:197], v[226:229], 0
	v_mfma_f32_16x16x32_bf16 v[56:59], v[198:201], v[218:221], v[56:59]
	v_mfma_f32_16x16x32_bf16 v[52:55], v[206:209], v[218:221], v[52:55]
	v_mfma_f32_16x16x32_bf16 v[36:39], v[206:209], v[222:225], v[36:39]
	v_mfma_f32_16x16x32_bf16 v[40:43], v[198:201], v[222:225], v[40:43]
	v_mfma_f32_16x16x32_bf16 v[8:11], v[198:201], v[238:241], v[8:11]
	v_mfma_f32_16x16x32_bf16 v[4:7], v[206:209], v[238:241], v[4:7]
	v_mfma_f32_16x16x32_bf16 v[20:23], v[206:209], v[234:237], v[20:23]
	v_mfma_f32_16x16x32_bf16 v[24:27], v[198:201], v[234:237], v[24:27]
	s_barrier
	ds_read_b128 v[168:171], v163
	ds_read_b128 v[174:177], v164
	ds_read_b128 v[178:181], v155
	ds_read_b128 v[182:185], v160
	ds_read_b128 v[194:197], v165
	ds_read_b128 v[198:201], v166
	ds_read_b128 v[202:205], v161
	ds_read_b128 v[206:209], v162
	s_mov_b32 m0, s34
	v_lshl_add_u64 v[242:243], s[70:71], 0, v[0:1]
	ds_read_b128 v[210:213], v153 offset:32768
	ds_read_b128 v[214:217], v153 offset:34816
	ds_read_b128 v[218:221], v154 offset:32768
	ds_read_b128 v[222:225], v154 offset:34816
	ds_read_b128 v[226:229], v153 offset:36864
	ds_read_b128 v[230:233], v153 offset:38912
	ds_read_b128 v[234:237], v154 offset:36864
	ds_read_b128 v[238:241], v154 offset:38912
	global_load_lds_dwordx4 v[242:243], off
	v_lshl_add_u64 v[244:245], v[242:243], 0, s[16:17]
	s_mov_b32 m0, s35
	s_nop 0
	global_load_lds_dwordx4 v[244:245], off
	v_lshl_add_u64 v[244:245], v[242:243], 0, s[0:1]
	s_mov_b32 m0, s38
	v_lshl_add_u64 v[242:243], v[242:243], 0, s[18:19]
	global_load_lds_dwordx4 v[244:245], off
	s_mov_b32 m0, s39
	s_nop 0
	global_load_lds_dwordx4 v[242:243], off
	s_waitcnt vmcnt(8)
	s_waitcnt lgkmcnt(0)
	s_barrier
	v_mfma_f32_16x16x32_bf16 v[128:131], v[168:171], v[210:213], v[128:131]
	v_mfma_f32_16x16x32_bf16 v[124:127], v[178:181], v[210:213], v[124:127]
	v_mfma_f32_16x16x32_bf16 v[108:111], v[178:181], v[214:217], v[108:111]
	v_mfma_f32_16x16x32_bf16 v[112:115], v[168:171], v[214:217], v[112:115]
	v_mfma_f32_16x16x32_bf16 v[80:83], v[168:171], v[230:233], v[80:83]
	v_mfma_f32_16x16x32_bf16 v[76:79], v[178:181], v[230:233], v[76:79]
	v_mfma_f32_16x16x32_bf16 v[92:95], v[178:181], v[226:229], v[92:95]
	v_mfma_f32_16x16x32_bf16 v[96:99], v[168:171], v[226:229], v[96:99]
	v_mfma_f32_16x16x32_bf16 v[128:131], v[174:177], v[218:221], v[128:131]
	v_mfma_f32_16x16x32_bf16 v[124:127], v[182:185], v[218:221], v[124:127]
	v_mfma_f32_16x16x32_bf16 v[108:111], v[182:185], v[222:225], v[108:111]
	v_mfma_f32_16x16x32_bf16 v[112:115], v[174:177], v[222:225], v[112:115]
	v_mfma_f32_16x16x32_bf16 v[80:83], v[174:177], v[238:241], v[80:83]
	v_mfma_f32_16x16x32_bf16 v[76:79], v[182:185], v[238:241], v[76:79]
	v_mfma_f32_16x16x32_bf16 v[92:95], v[182:185], v[234:237], v[92:95]
	v_mfma_f32_16x16x32_bf16 v[96:99], v[174:177], v[234:237], v[96:99]
	v_mfma_f32_16x16x32_bf16 v[120:123], v[194:197], v[210:213], v[120:123]
	v_mfma_f32_16x16x32_bf16 v[116:119], v[202:205], v[210:213], v[116:119]
	v_mfma_f32_16x16x32_bf16 v[100:103], v[202:205], v[214:217], v[100:103]
	v_mfma_f32_16x16x32_bf16 v[104:107], v[194:197], v[214:217], v[104:107]
	v_mfma_f32_16x16x32_bf16 v[72:75], v[194:197], v[230:233], v[72:75]
	v_mfma_f32_16x16x32_bf16 v[68:71], v[202:205], v[230:233], v[68:71]
	v_mfma_f32_16x16x32_bf16 v[84:87], v[202:205], v[226:229], v[84:87]
	v_mfma_f32_16x16x32_bf16 v[88:91], v[194:197], v[226:229], v[88:91]
	v_mfma_f32_16x16x32_bf16 v[120:123], v[198:201], v[218:221], v[120:123]
	v_mfma_f32_16x16x32_bf16 v[116:119], v[206:209], v[218:221], v[116:119]
	v_mfma_f32_16x16x32_bf16 v[100:103], v[206:209], v[222:225], v[100:103]
	v_mfma_f32_16x16x32_bf16 v[104:107], v[198:201], v[222:225], v[104:107]
	v_mfma_f32_16x16x32_bf16 v[72:75], v[198:201], v[238:241], v[72:75]
	v_mfma_f32_16x16x32_bf16 v[68:71], v[206:209], v[238:241], v[68:71]
	v_mfma_f32_16x16x32_bf16 v[84:87], v[206:209], v[234:237], v[84:87]
	v_mfma_f32_16x16x32_bf16 v[88:91], v[198:201], v[234:237], v[88:91]
	s_barrier
	s_add_i32 s70, s73, s3
	v_lshl_add_u64 v[242:243], v[140:141], 0, s[22:23]
	s_mov_b32 m0, s70
	ds_read_b128 v[210:213], v153 offset:49152
	ds_read_b128 v[214:217], v153 offset:51200
	ds_read_b128 v[218:221], v154 offset:49152
	ds_read_b128 v[222:225], v154 offset:51200
	ds_read_b128 v[226:229], v153 offset:53248
	ds_read_b128 v[230:233], v153 offset:55296
	ds_read_b128 v[234:237], v154 offset:53248
	ds_read_b128 v[238:241], v154 offset:55296
	global_load_lds_dwordx4 v[242:243], off
	v_lshl_add_u64 v[242:243], v[140:141], 0, s[24:25]
	s_add_i32 m0, s70, 0x2000
	s_add_i32 s70, s77, s3
	global_load_lds_dwordx4 v[242:243], off
	v_lshl_add_u64 v[242:243], v[140:141], 0, s[28:29]
	s_mov_b32 m0, s70
	v_lshl_add_u64 v[140:141], v[140:141], 0, s[36:37]
	global_load_lds_dwordx4 v[242:243], off
	s_add_i32 m0, s70, 0x2000
	s_nop 0
	global_load_lds_dwordx4 v[140:141], off
	s_waitcnt vmcnt(4)
	s_waitcnt lgkmcnt(0)
	s_barrier
	v_mfma_f32_16x16x32_bf16 v[64:67], v[168:171], v[210:213], v[64:67]
	v_mfma_f32_16x16x32_bf16 v[60:63], v[178:181], v[210:213], v[60:63]
	v_mfma_f32_16x16x32_bf16 v[44:47], v[178:181], v[214:217], v[44:47]
	v_mfma_f32_16x16x32_bf16 v[48:51], v[168:171], v[214:217], v[48:51]
	v_mfma_f32_16x16x32_bf16 v[16:19], v[168:171], v[230:233], v[16:19]
	v_mfma_f32_16x16x32_bf16 v[12:15], v[178:181], v[230:233], v[12:15]
	v_mfma_f32_16x16x32_bf16 v[28:31], v[178:181], v[226:229], v[28:31]
	v_mfma_f32_16x16x32_bf16 v[32:35], v[168:171], v[226:229], v[32:35]
	v_mfma_f32_16x16x32_bf16 v[64:67], v[174:177], v[218:221], v[64:67]
	v_mfma_f32_16x16x32_bf16 v[60:63], v[182:185], v[218:221], v[60:63]
	v_mfma_f32_16x16x32_bf16 v[44:47], v[182:185], v[222:225], v[44:47]
	v_mfma_f32_16x16x32_bf16 v[48:51], v[174:177], v[222:225], v[48:51]
	v_mfma_f32_16x16x32_bf16 v[16:19], v[174:177], v[238:241], v[16:19]
	v_mfma_f32_16x16x32_bf16 v[12:15], v[182:185], v[238:241], v[12:15]
	v_mfma_f32_16x16x32_bf16 v[28:31], v[182:185], v[234:237], v[28:31]
	v_mfma_f32_16x16x32_bf16 v[32:35], v[174:177], v[234:237], v[32:35]
	v_mfma_f32_16x16x32_bf16 v[56:59], v[194:197], v[210:213], v[56:59]
	v_mfma_f32_16x16x32_bf16 v[52:55], v[202:205], v[210:213], v[52:55]
	v_mfma_f32_16x16x32_bf16 v[36:39], v[202:205], v[214:217], v[36:39]
	v_mfma_f32_16x16x32_bf16 v[40:43], v[194:197], v[214:217], v[40:43]
	v_mfma_f32_16x16x32_bf16 v[8:11], v[194:197], v[230:233], v[8:11]
	v_mfma_f32_16x16x32_bf16 v[4:7], v[202:205], v[230:233], v[4:7]
	v_mfma_f32_16x16x32_bf16 v[20:23], v[202:205], v[226:229], v[20:23]
	v_mfma_f32_16x16x32_bf16 v[24:27], v[194:197], v[226:229], v[24:27]
	v_mfma_f32_16x16x32_bf16 v[56:59], v[198:201], v[218:221], v[56:59]
	v_mfma_f32_16x16x32_bf16 v[52:55], v[206:209], v[218:221], v[52:55]
	v_mfma_f32_16x16x32_bf16 v[36:39], v[206:209], v[222:225], v[36:39]
	v_mfma_f32_16x16x32_bf16 v[40:43], v[198:201], v[222:225], v[40:43]
	v_mfma_f32_16x16x32_bf16 v[8:11], v[198:201], v[238:241], v[8:11]
	v_mfma_f32_16x16x32_bf16 v[4:7], v[206:209], v[238:241], v[4:7]
	v_mfma_f32_16x16x32_bf16 v[20:23], v[206:209], v[234:237], v[20:23]
	v_mfma_f32_16x16x32_bf16 v[24:27], v[198:201], v[234:237], v[24:27]
	s_barrier
	s_add_i32 s83, s83, 2
	s_add_u32 s68, s68, 0x100
	s_addc_u32 s69, s69, 0
	s_cmp_gt_u32 s83, 13
.LBB0_1135:
	ds_read_b128 v[168:171], v145
	ds_read_b128 v[174:177], v146
	ds_read_b128 v[178:181], v147
	ds_read_b128 v[182:185], v148
	ds_read_b128 v[194:197], v149
	ds_read_b128 v[198:201], v150
	ds_read_b128 v[202:205], v151
	ds_read_b128 v[206:209], v152
	s_add_u32 s70, s26, s68
	s_addc_u32 s71, s27, s69
	s_add_u32 s70, s70, 0x100
	s_addc_u32 s71, s71, 0
	s_add_u32 s84, s81, s68
	s_addc_u32 s85, s82, s69
	s_cmpk_eq_i32 s68, 0x700
	s_cselect_b32 s85, s59, s85
	s_cselect_b32 s84, s80, s84
	s_cselect_b32 s71, s57, s71
	s_cselect_b32 s70, s79, s70
	v_lshl_add_u64 v[140:141], v[138:139], 0, s[68:69]
	v_lshl_add_u64 v[242:243], v[140:141], 0, s[22:23]
	s_add_i32 m0, s34, 0x8000
	s_mov_b64 s[86:87], 0x20080
	ds_read_b128 v[210:213], v153
	ds_read_b128 v[214:217], v153 offset:2048
	ds_read_b128 v[218:221], v154
	ds_read_b128 v[222:225], v154 offset:2048
	ds_read_b128 v[226:229], v153 offset:4096
	ds_read_b128 v[230:233], v153 offset:6144
	ds_read_b128 v[234:237], v154 offset:4096
	ds_read_b128 v[238:241], v154 offset:6144
	global_load_lds_dwordx4 v[242:243], off
	v_lshl_add_u64 v[242:243], v[140:141], 0, s[86:87]
	s_add_i32 m0, s34, 0xa000
	s_mov_b64 s[86:87], 0x60080
	global_load_lds_dwordx4 v[242:243], off
	v_lshl_add_u64 v[242:243], v[140:141], 0, s[24:25]
	s_add_i32 m0, s34, 0xc000
	v_lshl_add_u64 v[140:141], v[140:141], 0, s[86:87]
	global_load_lds_dwordx4 v[242:243], off
	s_add_i32 m0, s34, 0xe000
	s_nop 0
	global_load_lds_dwordx4 v[140:141], off
	s_waitcnt vmcnt(8)
	s_waitcnt lgkmcnt(0)
	s_barrier
	v_mfma_f32_16x16x32_bf16 v[128:131], v[168:171], v[210:213], v[128:131]
	v_mfma_f32_16x16x32_bf16 v[124:127], v[178:181], v[210:213], v[124:127]
	v_mfma_f32_16x16x32_bf16 v[108:111], v[178:181], v[214:217], v[108:111]
	v_mfma_f32_16x16x32_bf16 v[112:115], v[168:171], v[214:217], v[112:115]
	v_mfma_f32_16x16x32_bf16 v[80:83], v[168:171], v[230:233], v[80:83]
	v_mfma_f32_16x16x32_bf16 v[76:79], v[178:181], v[230:233], v[76:79]
	v_mfma_f32_16x16x32_bf16 v[92:95], v[178:181], v[226:229], v[92:95]
	v_mfma_f32_16x16x32_bf16 v[96:99], v[168:171], v[226:229], v[96:99]
	v_mfma_f32_16x16x32_bf16 v[128:131], v[174:177], v[218:221], v[128:131]
	v_mfma_f32_16x16x32_bf16 v[124:127], v[182:185], v[218:221], v[124:127]
	v_mfma_f32_16x16x32_bf16 v[108:111], v[182:185], v[222:225], v[108:111]
	v_mfma_f32_16x16x32_bf16 v[112:115], v[174:177], v[222:225], v[112:115]
	v_mfma_f32_16x16x32_bf16 v[80:83], v[174:177], v[238:241], v[80:83]
	v_mfma_f32_16x16x32_bf16 v[76:79], v[182:185], v[238:241], v[76:79]
	v_mfma_f32_16x16x32_bf16 v[92:95], v[182:185], v[234:237], v[92:95]
	v_mfma_f32_16x16x32_bf16 v[96:99], v[174:177], v[234:237], v[96:99]
	v_mfma_f32_16x16x32_bf16 v[120:123], v[194:197], v[210:213], v[120:123]
	v_mfma_f32_16x16x32_bf16 v[116:119], v[202:205], v[210:213], v[116:119]
	v_mfma_f32_16x16x32_bf16 v[100:103], v[202:205], v[214:217], v[100:103]
	v_mfma_f32_16x16x32_bf16 v[104:107], v[194:197], v[214:217], v[104:107]
	v_mfma_f32_16x16x32_bf16 v[72:75], v[194:197], v[230:233], v[72:75]
	v_mfma_f32_16x16x32_bf16 v[68:71], v[202:205], v[230:233], v[68:71]
	v_mfma_f32_16x16x32_bf16 v[84:87], v[202:205], v[226:229], v[84:87]
	v_mfma_f32_16x16x32_bf16 v[88:91], v[194:197], v[226:229], v[88:91]
	v_mfma_f32_16x16x32_bf16 v[120:123], v[198:201], v[218:221], v[120:123]
	v_mfma_f32_16x16x32_bf16 v[116:119], v[206:209], v[218:221], v[116:119]
	v_mfma_f32_16x16x32_bf16 v[100:103], v[206:209], v[222:225], v[100:103]
	v_mfma_f32_16x16x32_bf16 v[104:107], v[198:201], v[222:225], v[104:107]
	v_mfma_f32_16x16x32_bf16 v[72:75], v[198:201], v[238:241], v[72:75]
	v_mfma_f32_16x16x32_bf16 v[68:71], v[206:209], v[238:241], v[68:71]
	v_mfma_f32_16x16x32_bf16 v[84:87], v[206:209], v[234:237], v[84:87]
	v_mfma_f32_16x16x32_bf16 v[88:91], v[198:201], v[234:237], v[88:91]
	s_barrier
	v_lshl_add_u64 v[140:141], s[84:85], 0, v[158:159]
	s_add_i32 s84, s67, s3
	s_mov_b32 m0, s84
	ds_read_b128 v[210:213], v153 offset:16384
	ds_read_b128 v[214:217], v153 offset:18432
	ds_read_b128 v[218:221], v154 offset:16384
	ds_read_b128 v[222:225], v154 offset:18432
	ds_read_b128 v[226:229], v153 offset:20480
	ds_read_b128 v[230:233], v153 offset:22528
	ds_read_b128 v[234:237], v154 offset:20480
	ds_read_b128 v[238:241], v154 offset:22528
	global_load_lds_dwordx4 v[140:141], off
	v_lshl_add_u64 v[242:243], v[140:141], 0, s[0:1]
	s_add_i32 m0, s84, 0x2000
	s_add_i32 s84, s72, s3
	global_load_lds_dwordx4 v[242:243], off
	v_lshl_add_u64 v[242:243], v[140:141], 0, s[12:13]
	s_mov_b32 m0, s84
	s_nop 0
	global_load_lds_dwordx4 v[242:243], off
	v_lshl_add_u64 v[242:243], v[140:141], 0, s[14:15]
	s_add_i32 m0, s84, 0x2000
	s_nop 0
	global_load_lds_dwordx4 v[242:243], off
	s_waitcnt vmcnt(4)
	s_waitcnt lgkmcnt(0)
	s_barrier
	v_mfma_f32_16x16x32_bf16 v[64:67], v[168:171], v[210:213], v[64:67]
	v_mfma_f32_16x16x32_bf16 v[60:63], v[178:181], v[210:213], v[60:63]
	v_mfma_f32_16x16x32_bf16 v[44:47], v[178:181], v[214:217], v[44:47]
	v_mfma_f32_16x16x32_bf16 v[48:51], v[168:171], v[214:217], v[48:51]
	v_mfma_f32_16x16x32_bf16 v[16:19], v[168:171], v[230:233], v[16:19]
	v_mfma_f32_16x16x32_bf16 v[12:15], v[178:181], v[230:233], v[12:15]
	v_mfma_f32_16x16x32_bf16 v[28:31], v[178:181], v[226:229], v[28:31]
	v_mfma_f32_16x16x32_bf16 v[32:35], v[168:171], v[226:229], v[32:35]
	v_mfma_f32_16x16x32_bf16 v[64:67], v[174:177], v[218:221], v[64:67]
	v_mfma_f32_16x16x32_bf16 v[60:63], v[182:185], v[218:221], v[60:63]
	v_mfma_f32_16x16x32_bf16 v[44:47], v[182:185], v[222:225], v[44:47]
	v_mfma_f32_16x16x32_bf16 v[48:51], v[174:177], v[222:225], v[48:51]
	v_mfma_f32_16x16x32_bf16 v[16:19], v[174:177], v[238:241], v[16:19]
	v_mfma_f32_16x16x32_bf16 v[12:15], v[182:185], v[238:241], v[12:15]
	v_mfma_f32_16x16x32_bf16 v[28:31], v[182:185], v[234:237], v[28:31]
	v_mfma_f32_16x16x32_bf16 v[32:35], v[174:177], v[234:237], v[32:35]
	v_mfma_f32_16x16x32_bf16 v[56:59], v[194:197], v[210:213], v[56:59]
	v_mfma_f32_16x16x32_bf16 v[52:55], v[202:205], v[210:213], v[52:55]
	v_mfma_f32_16x16x32_bf16 v[36:39], v[202:205], v[214:217], v[36:39]
	v_mfma_f32_16x16x32_bf16 v[40:43], v[194:197], v[214:217], v[40:43]
	v_mfma_f32_16x16x32_bf16 v[8:11], v[194:197], v[230:233], v[8:11]
	v_mfma_f32_16x16x32_bf16 v[4:7], v[202:205], v[230:233], v[4:7]
	v_mfma_f32_16x16x32_bf16 v[20:23], v[202:205], v[226:229], v[20:23]
	v_mfma_f32_16x16x32_bf16 v[24:27], v[194:197], v[226:229], v[24:27]
	v_mfma_f32_16x16x32_bf16 v[56:59], v[198:201], v[218:221], v[56:59]
	v_mfma_f32_16x16x32_bf16 v[52:55], v[206:209], v[218:221], v[52:55]
	v_mfma_f32_16x16x32_bf16 v[36:39], v[206:209], v[222:225], v[36:39]
	v_mfma_f32_16x16x32_bf16 v[40:43], v[198:201], v[222:225], v[40:43]
	v_mfma_f32_16x16x32_bf16 v[8:11], v[198:201], v[238:241], v[8:11]
	v_mfma_f32_16x16x32_bf16 v[4:7], v[206:209], v[238:241], v[4:7]
	v_mfma_f32_16x16x32_bf16 v[20:23], v[206:209], v[234:237], v[20:23]
	v_mfma_f32_16x16x32_bf16 v[24:27], v[198:201], v[234:237], v[24:27]
	s_barrier
	ds_read_b128 v[168:171], v163
	ds_read_b128 v[174:177], v164
	ds_read_b128 v[178:181], v155
	ds_read_b128 v[182:185], v160
	ds_read_b128 v[194:197], v165
	ds_read_b128 v[198:201], v166
	ds_read_b128 v[202:205], v161
	ds_read_b128 v[206:209], v162
	s_mov_b32 m0, s34
	v_lshl_add_u64 v[242:243], s[70:71], 0, v[0:1]
	ds_read_b128 v[210:213], v153 offset:32768
	ds_read_b128 v[214:217], v153 offset:34816
	ds_read_b128 v[218:221], v154 offset:32768
	ds_read_b128 v[222:225], v154 offset:34816
	ds_read_b128 v[226:229], v153 offset:36864
	ds_read_b128 v[230:233], v153 offset:38912
	ds_read_b128 v[234:237], v154 offset:36864
	ds_read_b128 v[238:241], v154 offset:38912
	global_load_lds_dwordx4 v[242:243], off
	v_lshl_add_u64 v[244:245], v[242:243], 0, s[16:17]
	s_mov_b32 m0, s35
	s_nop 0
	global_load_lds_dwordx4 v[244:245], off
	v_lshl_add_u64 v[244:245], v[242:243], 0, s[0:1]
	s_mov_b32 m0, s38
	v_lshl_add_u64 v[242:243], v[242:243], 0, s[18:19]
	global_load_lds_dwordx4 v[244:245], off
	s_mov_b32 m0, s39
	s_nop 0
	global_load_lds_dwordx4 v[242:243], off
	s_waitcnt vmcnt(8)
	s_waitcnt lgkmcnt(0)
	s_barrier
	v_mfma_f32_16x16x32_bf16 v[128:131], v[168:171], v[210:213], v[128:131]
	v_mfma_f32_16x16x32_bf16 v[124:127], v[178:181], v[210:213], v[124:127]
	v_mfma_f32_16x16x32_bf16 v[108:111], v[178:181], v[214:217], v[108:111]
	v_mfma_f32_16x16x32_bf16 v[112:115], v[168:171], v[214:217], v[112:115]
	v_mfma_f32_16x16x32_bf16 v[80:83], v[168:171], v[230:233], v[80:83]
	v_mfma_f32_16x16x32_bf16 v[76:79], v[178:181], v[230:233], v[76:79]
	v_mfma_f32_16x16x32_bf16 v[92:95], v[178:181], v[226:229], v[92:95]
	v_mfma_f32_16x16x32_bf16 v[96:99], v[168:171], v[226:229], v[96:99]
	v_mfma_f32_16x16x32_bf16 v[128:131], v[174:177], v[218:221], v[128:131]
	v_mfma_f32_16x16x32_bf16 v[124:127], v[182:185], v[218:221], v[124:127]
	v_mfma_f32_16x16x32_bf16 v[108:111], v[182:185], v[222:225], v[108:111]
	v_mfma_f32_16x16x32_bf16 v[112:115], v[174:177], v[222:225], v[112:115]
	v_mfma_f32_16x16x32_bf16 v[80:83], v[174:177], v[238:241], v[80:83]
	v_mfma_f32_16x16x32_bf16 v[76:79], v[182:185], v[238:241], v[76:79]
	v_mfma_f32_16x16x32_bf16 v[92:95], v[182:185], v[234:237], v[92:95]
	v_mfma_f32_16x16x32_bf16 v[96:99], v[174:177], v[234:237], v[96:99]
	v_mfma_f32_16x16x32_bf16 v[120:123], v[194:197], v[210:213], v[120:123]
	v_mfma_f32_16x16x32_bf16 v[116:119], v[202:205], v[210:213], v[116:119]
	v_mfma_f32_16x16x32_bf16 v[100:103], v[202:205], v[214:217], v[100:103]
	v_mfma_f32_16x16x32_bf16 v[104:107], v[194:197], v[214:217], v[104:107]
	v_mfma_f32_16x16x32_bf16 v[72:75], v[194:197], v[230:233], v[72:75]
	v_mfma_f32_16x16x32_bf16 v[68:71], v[202:205], v[230:233], v[68:71]
	v_mfma_f32_16x16x32_bf16 v[84:87], v[202:205], v[226:229], v[84:87]
	v_mfma_f32_16x16x32_bf16 v[88:91], v[194:197], v[226:229], v[88:91]
	v_mfma_f32_16x16x32_bf16 v[120:123], v[198:201], v[218:221], v[120:123]
	v_mfma_f32_16x16x32_bf16 v[116:119], v[206:209], v[218:221], v[116:119]
	v_mfma_f32_16x16x32_bf16 v[100:103], v[206:209], v[222:225], v[100:103]
	v_mfma_f32_16x16x32_bf16 v[104:107], v[198:201], v[222:225], v[104:107]
	v_mfma_f32_16x16x32_bf16 v[72:75], v[198:201], v[238:241], v[72:75]
	v_mfma_f32_16x16x32_bf16 v[68:71], v[206:209], v[238:241], v[68:71]
	v_mfma_f32_16x16x32_bf16 v[84:87], v[206:209], v[234:237], v[84:87]
	v_mfma_f32_16x16x32_bf16 v[88:91], v[198:201], v[234:237], v[88:91]
	s_barrier
	s_add_i32 s70, s73, s3
	v_lshl_add_u64 v[242:243], v[140:141], 0, s[22:23]
	s_mov_b32 m0, s70
	ds_read_b128 v[210:213], v153 offset:49152
	ds_read_b128 v[214:217], v153 offset:51200
	ds_read_b128 v[218:221], v154 offset:49152
	ds_read_b128 v[222:225], v154 offset:51200
	ds_read_b128 v[226:229], v153 offset:53248
	ds_read_b128 v[230:233], v153 offset:55296
	ds_read_b128 v[234:237], v154 offset:53248
	ds_read_b128 v[238:241], v154 offset:55296
	global_load_lds_dwordx4 v[242:243], off
	v_lshl_add_u64 v[242:243], v[140:141], 0, s[24:25]
	s_add_i32 m0, s70, 0x2000
	s_add_i32 s70, s77, s3
	global_load_lds_dwordx4 v[242:243], off
	v_lshl_add_u64 v[242:243], v[140:141], 0, s[28:29]
	s_mov_b32 m0, s70
	v_lshl_add_u64 v[140:141], v[140:141], 0, s[36:37]
	global_load_lds_dwordx4 v[242:243], off
	s_add_i32 m0, s70, 0x2000
	s_nop 0
	global_load_lds_dwordx4 v[140:141], off
	s_waitcnt vmcnt(4)
	s_waitcnt lgkmcnt(0)
	s_barrier
	v_mfma_f32_16x16x32_bf16 v[64:67], v[168:171], v[210:213], v[64:67]
	v_mfma_f32_16x16x32_bf16 v[60:63], v[178:181], v[210:213], v[60:63]
	v_mfma_f32_16x16x32_bf16 v[44:47], v[178:181], v[214:217], v[44:47]
	v_mfma_f32_16x16x32_bf16 v[48:51], v[168:171], v[214:217], v[48:51]
	v_mfma_f32_16x16x32_bf16 v[16:19], v[168:171], v[230:233], v[16:19]
	v_mfma_f32_16x16x32_bf16 v[12:15], v[178:181], v[230:233], v[12:15]
	v_mfma_f32_16x16x32_bf16 v[28:31], v[178:181], v[226:229], v[28:31]
	v_mfma_f32_16x16x32_bf16 v[32:35], v[168:171], v[226:229], v[32:35]
	v_mfma_f32_16x16x32_bf16 v[64:67], v[174:177], v[218:221], v[64:67]
	v_mfma_f32_16x16x32_bf16 v[60:63], v[182:185], v[218:221], v[60:63]
	v_mfma_f32_16x16x32_bf16 v[44:47], v[182:185], v[222:225], v[44:47]
	v_mfma_f32_16x16x32_bf16 v[48:51], v[174:177], v[222:225], v[48:51]
	v_mfma_f32_16x16x32_bf16 v[16:19], v[174:177], v[238:241], v[16:19]
	v_mfma_f32_16x16x32_bf16 v[12:15], v[182:185], v[238:241], v[12:15]
	v_mfma_f32_16x16x32_bf16 v[28:31], v[182:185], v[234:237], v[28:31]
	v_mfma_f32_16x16x32_bf16 v[32:35], v[174:177], v[234:237], v[32:35]
	v_mfma_f32_16x16x32_bf16 v[56:59], v[194:197], v[210:213], v[56:59]
	v_mfma_f32_16x16x32_bf16 v[52:55], v[202:205], v[210:213], v[52:55]
	v_mfma_f32_16x16x32_bf16 v[36:39], v[202:205], v[214:217], v[36:39]
	v_mfma_f32_16x16x32_bf16 v[40:43], v[194:197], v[214:217], v[40:43]
	v_mfma_f32_16x16x32_bf16 v[8:11], v[194:197], v[230:233], v[8:11]
	v_mfma_f32_16x16x32_bf16 v[4:7], v[202:205], v[230:233], v[4:7]
	v_mfma_f32_16x16x32_bf16 v[20:23], v[202:205], v[226:229], v[20:23]
	v_mfma_f32_16x16x32_bf16 v[24:27], v[194:197], v[226:229], v[24:27]
	v_mfma_f32_16x16x32_bf16 v[56:59], v[198:201], v[218:221], v[56:59]
	v_mfma_f32_16x16x32_bf16 v[52:55], v[206:209], v[218:221], v[52:55]
	v_mfma_f32_16x16x32_bf16 v[36:39], v[206:209], v[222:225], v[36:39]
	v_mfma_f32_16x16x32_bf16 v[40:43], v[198:201], v[222:225], v[40:43]
	v_mfma_f32_16x16x32_bf16 v[8:11], v[198:201], v[238:241], v[8:11]
	v_mfma_f32_16x16x32_bf16 v[4:7], v[206:209], v[238:241], v[4:7]
	v_mfma_f32_16x16x32_bf16 v[20:23], v[206:209], v[234:237], v[20:23]
	v_mfma_f32_16x16x32_bf16 v[24:27], v[198:201], v[234:237], v[24:27]
	s_barrier
	s_add_i32 s83, s83, 2
	s_add_u32 s68, s68, 0x100
	s_addc_u32 s69, s69, 0
	s_cmp_gt_u32 s83, 13
	s_cbranch_scc0 .LBB0_1135
	s_and_b64 vcc, exec, s[40:41]
	s_cbranch_vccz .LBB0_1138
	s_barrier

.LBB0_1371:
	v_add_u32_e32 v147, s64, v143
	v_add_u32_e32 v152, s64, v144
	ds_read_b128 v[148:151], v147
	ds_read_b128 v[152:155], v152
	v_add_u32_e32 v147, s65, v143
	v_add_u32_e32 v162, s65, v144
	s_add_u32 s58, s18, s56
	ds_read_b128 v[158:161], v147
	ds_read_b128 v[162:165], v162
	v_add_u32_e32 v147, s66, v143
	s_addc_u32 s59, s19, s57
	v_add_u32_e32 v166, s66, v144
	ds_read_b128 v[170:173], v147
	ds_read_b128 v[174:177], v166
	v_add_u32_e32 v147, s67, v143
	s_add_u32 s58, s58, 0x100
	v_add_u32_e32 v166, s67, v144
	ds_read_b128 v[178:181], v147
	ds_read_b128 v[182:185], v166
	s_addc_u32 s59, s59, 0
	s_add_u32 s78, s53, s56
	s_addc_u32 s79, s72, s57
	s_cmpk_eq_i32 s56, 0x1f00
	s_cselect_b32 s79, s49, s79
	s_cselect_b32 s78, s76, s78
	s_cselect_b32 s59, s51, s59
	s_cselect_b32 s58, s73, s58
	v_lshl_add_u64 v[166:167], v[140:141], 0, s[56:57]
	v_lshl_add_u64 v[218:219], v[166:167], 0, s[24:25]
	s_add_i32 m0, s35, 0x8000
	ds_read_b128 v[186:189], v145
	ds_read_b128 v[190:193], v145 offset:2048
	ds_read_b128 v[194:197], v146
	ds_read_b128 v[198:201], v146 offset:2048
	ds_read_b128 v[202:205], v145 offset:4096
	ds_read_b128 v[206:209], v145 offset:6144
	ds_read_b128 v[210:213], v146 offset:4096
	ds_read_b128 v[214:217], v146 offset:6144
	global_load_lds_dwordx4 v[218:219], off
	v_lshl_add_u64 v[218:219], v[166:167], 0, s[44:45]
	s_add_i32 m0, s35, 0xa000
	s_nop 0
	global_load_lds_dwordx4 v[218:219], off
	v_lshl_add_u64 v[218:219], v[166:167], 0, s[28:29]
	s_add_i32 m0, s35, 0xc000
	v_lshl_add_u64 v[166:167], v[166:167], 0, s[46:47]
	global_load_lds_dwordx4 v[218:219], off
	s_add_i32 m0, s35, 0xe000
	s_nop 0
	global_load_lds_dwordx4 v[166:167], off
	s_waitcnt vmcnt(8)
	s_waitcnt lgkmcnt(0)
	s_barrier
	v_mfma_f32_16x16x32_bf16 v[128:131], v[148:151], v[186:189], v[128:131]
	v_mfma_f32_16x16x32_bf16 v[124:127], v[158:161], v[186:189], v[124:127]
	v_mfma_f32_16x16x32_bf16 v[108:111], v[158:161], v[190:193], v[108:111]
	v_mfma_f32_16x16x32_bf16 v[112:115], v[148:151], v[190:193], v[112:115]
	v_mfma_f32_16x16x32_bf16 v[80:83], v[148:151], v[206:209], v[80:83]
	v_mfma_f32_16x16x32_bf16 v[76:79], v[158:161], v[206:209], v[76:79]
	v_mfma_f32_16x16x32_bf16 v[92:95], v[158:161], v[202:205], v[92:95]
	v_mfma_f32_16x16x32_bf16 v[96:99], v[148:151], v[202:205], v[96:99]
	v_mfma_f32_16x16x32_bf16 v[128:131], v[152:155], v[194:197], v[128:131]
	v_mfma_f32_16x16x32_bf16 v[124:127], v[162:165], v[194:197], v[124:127]
	v_mfma_f32_16x16x32_bf16 v[108:111], v[162:165], v[198:201], v[108:111]
	v_mfma_f32_16x16x32_bf16 v[112:115], v[152:155], v[198:201], v[112:115]
	v_mfma_f32_16x16x32_bf16 v[80:83], v[152:155], v[214:217], v[80:83]
	v_mfma_f32_16x16x32_bf16 v[76:79], v[162:165], v[214:217], v[76:79]
	v_mfma_f32_16x16x32_bf16 v[92:95], v[162:165], v[210:213], v[92:95]
	v_mfma_f32_16x16x32_bf16 v[96:99], v[152:155], v[210:213], v[96:99]
	v_mfma_f32_16x16x32_bf16 v[120:123], v[170:173], v[186:189], v[120:123]
	v_mfma_f32_16x16x32_bf16 v[116:119], v[178:181], v[186:189], v[116:119]
	v_mfma_f32_16x16x32_bf16 v[100:103], v[178:181], v[190:193], v[100:103]
	v_mfma_f32_16x16x32_bf16 v[104:107], v[170:173], v[190:193], v[104:107]
	v_mfma_f32_16x16x32_bf16 v[72:75], v[170:173], v[206:209], v[72:75]
	v_mfma_f32_16x16x32_bf16 v[68:71], v[178:181], v[206:209], v[68:71]
	v_mfma_f32_16x16x32_bf16 v[84:87], v[178:181], v[202:205], v[84:87]
	v_mfma_f32_16x16x32_bf16 v[88:91], v[170:173], v[202:205], v[88:91]
	v_mfma_f32_16x16x32_bf16 v[120:123], v[174:177], v[194:197], v[120:123]
	v_mfma_f32_16x16x32_bf16 v[116:119], v[182:185], v[194:197], v[116:119]
	v_mfma_f32_16x16x32_bf16 v[100:103], v[182:185], v[198:201], v[100:103]
	v_mfma_f32_16x16x32_bf16 v[104:107], v[174:177], v[198:201], v[104:107]
	v_mfma_f32_16x16x32_bf16 v[72:75], v[174:177], v[214:217], v[72:75]
	v_mfma_f32_16x16x32_bf16 v[68:71], v[182:185], v[214:217], v[68:71]
	v_mfma_f32_16x16x32_bf16 v[84:87], v[182:185], v[210:213], v[84:87]
	v_mfma_f32_16x16x32_bf16 v[88:91], v[174:177], v[210:213], v[88:91]
	s_barrier
	v_lshl_add_u64 v[166:167], s[78:79], 0, v[132:133]
	s_add_i32 s78, s64, s34
	s_mov_b32 m0, s78
	ds_read_b128 v[186:189], v145 offset:16384
	ds_read_b128 v[190:193], v145 offset:18432
	ds_read_b128 v[194:197], v146 offset:16384
	ds_read_b128 v[198:201], v146 offset:18432
	ds_read_b128 v[202:205], v145 offset:20480
	ds_read_b128 v[206:209], v145 offset:22528
	ds_read_b128 v[210:213], v146 offset:20480
	ds_read_b128 v[214:217], v146 offset:22528
	global_load_lds_dwordx4 v[166:167], off
	v_lshl_add_u64 v[218:219], v[166:167], 0, s[10:11]
	s_add_i32 m0, s78, 0x2000
	s_add_i32 s78, s66, s34
	global_load_lds_dwordx4 v[218:219], off
	v_lshl_add_u64 v[218:219], v[166:167], 0, s[14:15]
	s_mov_b32 m0, s78
	s_nop 0
	global_load_lds_dwordx4 v[218:219], off
	v_lshl_add_u64 v[218:219], v[166:167], 0, s[16:17]
	s_add_i32 m0, s78, 0x2000
	s_nop 0
	global_load_lds_dwordx4 v[218:219], off
	s_waitcnt vmcnt(4)
	s_waitcnt lgkmcnt(0)
	s_barrier
	v_mfma_f32_16x16x32_bf16 v[64:67], v[148:151], v[186:189], v[64:67]
	v_mfma_f32_16x16x32_bf16 v[60:63], v[158:161], v[186:189], v[60:63]
	v_mfma_f32_16x16x32_bf16 v[44:47], v[158:161], v[190:193], v[44:47]
	v_mfma_f32_16x16x32_bf16 v[48:51], v[148:151], v[190:193], v[48:51]
	v_mfma_f32_16x16x32_bf16 v[16:19], v[148:151], v[206:209], v[16:19]
	v_mfma_f32_16x16x32_bf16 v[12:15], v[158:161], v[206:209], v[12:15]
	v_mfma_f32_16x16x32_bf16 v[28:31], v[158:161], v[202:205], v[28:31]
	v_mfma_f32_16x16x32_bf16 v[32:35], v[148:151], v[202:205], v[32:35]
	v_mfma_f32_16x16x32_bf16 v[64:67], v[152:155], v[194:197], v[64:67]
	v_mfma_f32_16x16x32_bf16 v[60:63], v[162:165], v[194:197], v[60:63]
	v_mfma_f32_16x16x32_bf16 v[44:47], v[162:165], v[198:201], v[44:47]
	v_mfma_f32_16x16x32_bf16 v[48:51], v[152:155], v[198:201], v[48:51]
	v_mfma_f32_16x16x32_bf16 v[16:19], v[152:155], v[214:217], v[16:19]
	v_mfma_f32_16x16x32_bf16 v[12:15], v[162:165], v[214:217], v[12:15]
	v_mfma_f32_16x16x32_bf16 v[28:31], v[162:165], v[210:213], v[28:31]
	v_mfma_f32_16x16x32_bf16 v[32:35], v[152:155], v[210:213], v[32:35]
	v_mfma_f32_16x16x32_bf16 v[56:59], v[170:173], v[186:189], v[56:59]
	v_mfma_f32_16x16x32_bf16 v[52:55], v[178:181], v[186:189], v[52:55]
	v_mfma_f32_16x16x32_bf16 v[36:39], v[178:181], v[190:193], v[36:39]
	v_mfma_f32_16x16x32_bf16 v[40:43], v[170:173], v[190:193], v[40:43]
	v_mfma_f32_16x16x32_bf16 v[8:11], v[170:173], v[206:209], v[8:11]
	v_mfma_f32_16x16x32_bf16 v[4:7], v[178:181], v[206:209], v[4:7]
	v_mfma_f32_16x16x32_bf16 v[20:23], v[178:181], v[202:205], v[20:23]
	v_mfma_f32_16x16x32_bf16 v[24:27], v[170:173], v[202:205], v[24:27]
	v_mfma_f32_16x16x32_bf16 v[56:59], v[174:177], v[194:197], v[56:59]
	v_mfma_f32_16x16x32_bf16 v[52:55], v[182:185], v[194:197], v[52:55]
	v_mfma_f32_16x16x32_bf16 v[36:39], v[182:185], v[198:201], v[36:39]
	v_mfma_f32_16x16x32_bf16 v[40:43], v[174:177], v[198:201], v[40:43]
	v_mfma_f32_16x16x32_bf16 v[8:11], v[174:177], v[214:217], v[8:11]
	v_mfma_f32_16x16x32_bf16 v[4:7], v[182:185], v[214:217], v[4:7]
	v_mfma_f32_16x16x32_bf16 v[20:23], v[182:185], v[210:213], v[20:23]
	v_mfma_f32_16x16x32_bf16 v[24:27], v[174:177], v[210:213], v[24:27]
	s_barrier
	v_add_u32_e32 v147, s70, v143
	v_add_u32_e32 v152, s70, v144
	ds_read_b128 v[148:151], v147
	ds_read_b128 v[152:155], v152
	v_add_u32_e32 v147, s68, v143
	v_add_u32_e32 v162, s68, v144
	ds_read_b128 v[158:161], v147
	ds_read_b128 v[162:165], v162
	v_add_u32_e32 v147, s71, v143
	v_add_u32_e32 v169, s71, v144
	ds_read_b128 v[170:173], v147
	ds_read_b128 v[174:177], v169
	v_add_u32_e32 v147, s69, v143
	v_add_u32_e32 v169, s69, v144
	ds_read_b128 v[178:181], v147
	ds_read_b128 v[182:185], v169
	s_mov_b32 m0, s35
	v_lshl_add_u64 v[218:219], s[58:59], 0, v[0:1]
	ds_read_b128 v[186:189], v145 offset:32768
	ds_read_b128 v[190:193], v145 offset:34816
	ds_read_b128 v[194:197], v146 offset:32768
	ds_read_b128 v[198:201], v146 offset:34816
	ds_read_b128 v[202:205], v145 offset:36864
	ds_read_b128 v[206:209], v145 offset:38912
	ds_read_b128 v[210:213], v146 offset:36864
	ds_read_b128 v[214:217], v146 offset:38912
	global_load_lds_dwordx4 v[218:219], off
	v_lshl_add_u64 v[220:221], v[218:219], 0, s[20:21]
	s_mov_b32 m0, s39
	s_nop 0
	global_load_lds_dwordx4 v[220:221], off
	v_lshl_add_u64 v[220:221], v[218:219], 0, s[10:11]
	s_mov_b32 m0, s60
	v_lshl_add_u64 v[218:219], v[218:219], 0, s[22:23]
	global_load_lds_dwordx4 v[220:221], off
	s_mov_b32 m0, s61
	s_nop 0
	global_load_lds_dwordx4 v[218:219], off
	s_waitcnt vmcnt(8)
	s_waitcnt lgkmcnt(0)
	s_barrier
	v_mfma_f32_16x16x32_bf16 v[128:131], v[148:151], v[186:189], v[128:131]
	v_mfma_f32_16x16x32_bf16 v[124:127], v[158:161], v[186:189], v[124:127]
	v_mfma_f32_16x16x32_bf16 v[108:111], v[158:161], v[190:193], v[108:111]
	v_mfma_f32_16x16x32_bf16 v[112:115], v[148:151], v[190:193], v[112:115]
	v_mfma_f32_16x16x32_bf16 v[80:83], v[148:151], v[206:209], v[80:83]
	v_mfma_f32_16x16x32_bf16 v[76:79], v[158:161], v[206:209], v[76:79]
	v_mfma_f32_16x16x32_bf16 v[92:95], v[158:161], v[202:205], v[92:95]
	v_mfma_f32_16x16x32_bf16 v[96:99], v[148:151], v[202:205], v[96:99]
	v_mfma_f32_16x16x32_bf16 v[128:131], v[152:155], v[194:197], v[128:131]
	v_mfma_f32_16x16x32_bf16 v[124:127], v[162:165], v[194:197], v[124:127]
	v_mfma_f32_16x16x32_bf16 v[108:111], v[162:165], v[198:201], v[108:111]
	v_mfma_f32_16x16x32_bf16 v[112:115], v[152:155], v[198:201], v[112:115]
	v_mfma_f32_16x16x32_bf16 v[80:83], v[152:155], v[214:217], v[80:83]
	v_mfma_f32_16x16x32_bf16 v[76:79], v[162:165], v[214:217], v[76:79]
	v_mfma_f32_16x16x32_bf16 v[92:95], v[162:165], v[210:213], v[92:95]
	v_mfma_f32_16x16x32_bf16 v[96:99], v[152:155], v[210:213], v[96:99]
	v_mfma_f32_16x16x32_bf16 v[120:123], v[170:173], v[186:189], v[120:123]
	v_mfma_f32_16x16x32_bf16 v[116:119], v[178:181], v[186:189], v[116:119]
	v_mfma_f32_16x16x32_bf16 v[100:103], v[178:181], v[190:193], v[100:103]
	v_mfma_f32_16x16x32_bf16 v[104:107], v[170:173], v[190:193], v[104:107]
	v_mfma_f32_16x16x32_bf16 v[72:75], v[170:173], v[206:209], v[72:75]
	v_mfma_f32_16x16x32_bf16 v[68:71], v[178:181], v[206:209], v[68:71]
	v_mfma_f32_16x16x32_bf16 v[84:87], v[178:181], v[202:205], v[84:87]
	v_mfma_f32_16x16x32_bf16 v[88:91], v[170:173], v[202:205], v[88:91]
	v_mfma_f32_16x16x32_bf16 v[120:123], v[174:177], v[194:197], v[120:123]
	v_mfma_f32_16x16x32_bf16 v[116:119], v[182:185], v[194:197], v[116:119]
	v_mfma_f32_16x16x32_bf16 v[100:103], v[182:185], v[198:201], v[100:103]
	v_mfma_f32_16x16x32_bf16 v[104:107], v[174:177], v[198:201], v[104:107]
	v_mfma_f32_16x16x32_bf16 v[72:75], v[174:177], v[214:217], v[72:75]
	v_mfma_f32_16x16x32_bf16 v[68:71], v[182:185], v[214:217], v[68:71]
	v_mfma_f32_16x16x32_bf16 v[84:87], v[182:185], v[210:213], v[84:87]
	v_mfma_f32_16x16x32_bf16 v[88:91], v[174:177], v[210:213], v[88:91]
	s_barrier
	s_add_i32 s58, s70, s34
	v_lshl_add_u64 v[218:219], v[166:167], 0, s[24:25]
	s_mov_b32 m0, s58
	ds_read_b128 v[186:189], v145 offset:49152
	ds_read_b128 v[190:193], v145 offset:51200
	ds_read_b128 v[194:197], v146 offset:49152
	ds_read_b128 v[198:201], v146 offset:51200
	ds_read_b128 v[202:205], v145 offset:53248
	ds_read_b128 v[206:209], v145 offset:55296
	ds_read_b128 v[210:213], v146 offset:53248
	ds_read_b128 v[214:217], v146 offset:55296
	global_load_lds_dwordx4 v[218:219], off
	v_lshl_add_u64 v[218:219], v[166:167], 0, s[28:29]
	s_add_i32 m0, s58, 0x2000
	s_add_i32 s58, s71, s34
	global_load_lds_dwordx4 v[218:219], off
	v_lshl_add_u64 v[218:219], v[166:167], 0, s[36:37]
	s_mov_b32 m0, s58
	v_lshl_add_u64 v[166:167], v[166:167], 0, s[40:41]
	global_load_lds_dwordx4 v[218:219], off
	s_add_i32 m0, s58, 0x2000
	s_nop 0
	global_load_lds_dwordx4 v[166:167], off
	s_waitcnt vmcnt(4)
	s_waitcnt lgkmcnt(0)
	s_barrier
	v_mfma_f32_16x16x32_bf16 v[64:67], v[148:151], v[186:189], v[64:67]
	v_mfma_f32_16x16x32_bf16 v[60:63], v[158:161], v[186:189], v[60:63]
	v_mfma_f32_16x16x32_bf16 v[44:47], v[158:161], v[190:193], v[44:47]
	v_mfma_f32_16x16x32_bf16 v[48:51], v[148:151], v[190:193], v[48:51]
	v_mfma_f32_16x16x32_bf16 v[16:19], v[148:151], v[206:209], v[16:19]
	v_mfma_f32_16x16x32_bf16 v[12:15], v[158:161], v[206:209], v[12:15]
	v_mfma_f32_16x16x32_bf16 v[28:31], v[158:161], v[202:205], v[28:31]
	v_mfma_f32_16x16x32_bf16 v[32:35], v[148:151], v[202:205], v[32:35]
	v_mfma_f32_16x16x32_bf16 v[64:67], v[152:155], v[194:197], v[64:67]
	v_mfma_f32_16x16x32_bf16 v[60:63], v[162:165], v[194:197], v[60:63]
	v_mfma_f32_16x16x32_bf16 v[44:47], v[162:165], v[198:201], v[44:47]
	v_mfma_f32_16x16x32_bf16 v[48:51], v[152:155], v[198:201], v[48:51]
	v_mfma_f32_16x16x32_bf16 v[16:19], v[152:155], v[214:217], v[16:19]
	v_mfma_f32_16x16x32_bf16 v[12:15], v[162:165], v[214:217], v[12:15]
	v_mfma_f32_16x16x32_bf16 v[28:31], v[162:165], v[210:213], v[28:31]
	v_mfma_f32_16x16x32_bf16 v[32:35], v[152:155], v[210:213], v[32:35]
	v_mfma_f32_16x16x32_bf16 v[56:59], v[170:173], v[186:189], v[56:59]
	v_mfma_f32_16x16x32_bf16 v[52:55], v[178:181], v[186:189], v[52:55]
	v_mfma_f32_16x16x32_bf16 v[36:39], v[178:181], v[190:193], v[36:39]
	v_mfma_f32_16x16x32_bf16 v[40:43], v[170:173], v[190:193], v[40:43]
	v_mfma_f32_16x16x32_bf16 v[8:11], v[170:173], v[206:209], v[8:11]
	v_mfma_f32_16x16x32_bf16 v[4:7], v[178:181], v[206:209], v[4:7]
	v_mfma_f32_16x16x32_bf16 v[20:23], v[178:181], v[202:205], v[20:23]
	v_mfma_f32_16x16x32_bf16 v[24:27], v[170:173], v[202:205], v[24:27]
	v_mfma_f32_16x16x32_bf16 v[56:59], v[174:177], v[194:197], v[56:59]
	v_mfma_f32_16x16x32_bf16 v[52:55], v[182:185], v[194:197], v[52:55]
	v_mfma_f32_16x16x32_bf16 v[36:39], v[182:185], v[198:201], v[36:39]
	v_mfma_f32_16x16x32_bf16 v[40:43], v[174:177], v[198:201], v[40:43]
	v_mfma_f32_16x16x32_bf16 v[8:11], v[174:177], v[214:217], v[8:11]
	v_mfma_f32_16x16x32_bf16 v[4:7], v[182:185], v[214:217], v[4:7]
	v_mfma_f32_16x16x32_bf16 v[20:23], v[182:185], v[210:213], v[20:23]
	v_mfma_f32_16x16x32_bf16 v[24:27], v[174:177], v[210:213], v[24:27]
	s_barrier
	s_add_i32 s77, s77, 2
	s_add_u32 s56, s56, 0x100
	s_addc_u32 s57, s57, 0
	s_cmp_gt_u32 s77, 61
	s_cbranch_scc0 .LBB0_1371
	s_add_u32 s56, s53, 0xffffff00
	s_addc_u32 s57, s72, -1
	s_andn2_b64 vcc, exec, s[6:7]
	s_cbranch_vccnz .LBB0_1362
	v_mov_b32_e32 v4, 0
	s_mov_b32 s0, s48
	s_mov_b32 s8, s50
	s_mov_b64 s[18:19], s[54:55]
	s_mov_b32 s63, s52
	v_mov_b32_e32 v5, v4
	v_mov_b32_e32 v6, v4
	v_mov_b32_e32 v7, v4
	v_mov_b32_e32 v8, v4
	v_mov_b32_e32 v9, v4
	v_mov_b32_e32 v10, v4
	v_mov_b32_e32 v11, v4
	v_mov_b32_e32 v20, v4
	v_mov_b32_e32 v21, v4
	v_mov_b32_e32 v22, v4
	v_mov_b32_e32 v23, v4
	v_mov_b32_e32 v24, v4
	v_mov_b32_e32 v25, v4
	v_mov_b32_e32 v26, v4
	v_mov_b32_e32 v27, v4
	v_mov_b32_e32 v36, v4
	v_mov_b32_e32 v37, v4
	v_mov_b32_e32 v38, v4
	v_mov_b32_e32 v39, v4
	v_mov_b32_e32 v40, v4
	v_mov_b32_e32 v41, v4
	v_mov_b32_e32 v42, v4
	v_mov_b32_e32 v43, v4
	v_mov_b32_e32 v52, v4
	v_mov_b32_e32 v53, v4
	v_mov_b32_e32 v54, v4
	v_mov_b32_e32 v55, v4
	v_mov_b32_e32 v56, v4
	v_mov_b32_e32 v57, v4
	v_mov_b32_e32 v58, v4
	v_mov_b32_e32 v59, v4
	v_mov_b32_e32 v12, v4
	v_mov_b32_e32 v13, v4
	v_mov_b32_e32 v14, v4
	v_mov_b32_e32 v15, v4
	v_mov_b32_e32 v16, v4
	v_mov_b32_e32 v17, v4
	v_mov_b32_e32 v18, v4
	v_mov_b32_e32 v19, v4
	v_mov_b32_e32 v28, v4
	v_mov_b32_e32 v29, v4
	v_mov_b32_e32 v30, v4
	v_mov_b32_e32 v31, v4
	v_mov_b32_e32 v32, v4
	v_mov_b32_e32 v33, v4
	v_mov_b32_e32 v34, v4
	v_mov_b32_e32 v35, v4
	v_mov_b32_e32 v44, v4
	v_mov_b32_e32 v45, v4
	v_mov_b32_e32 v46, v4
	v_mov_b32_e32 v47, v4
	v_mov_b32_e32 v48, v4
	v_mov_b32_e32 v49, v4
	v_mov_b32_e32 v50, v4
	v_mov_b32_e32 v51, v4
	v_mov_b32_e32 v60, v4
	v_mov_b32_e32 v61, v4
	v_mov_b32_e32 v62, v4
	v_mov_b32_e32 v63, v4
	v_mov_b32_e32 v64, v4
	v_mov_b32_e32 v65, v4
	v_mov_b32_e32 v66, v4
	v_mov_b32_e32 v67, v4
	v_mov_b32_e32 v68, v4
	v_mov_b32_e32 v69, v4
	v_mov_b32_e32 v70, v4
	v_mov_b32_e32 v71, v4
	v_mov_b32_e32 v72, v4
	v_mov_b32_e32 v73, v4
	v_mov_b32_e32 v74, v4
	v_mov_b32_e32 v75, v4
	v_mov_b32_e32 v84, v4
	v_mov_b32_e32 v85, v4
	v_mov_b32_e32 v86, v4
	v_mov_b32_e32 v87, v4
	v_mov_b32_e32 v88, v4
	v_mov_b32_e32 v89, v4
	v_mov_b32_e32 v90, v4
	v_mov_b32_e32 v91, v4
	v_mov_b32_e32 v100, v4
	v_mov_b32_e32 v101, v4
	v_mov_b32_e32 v102, v4
	v_mov_b32_e32 v103, v4
	v_mov_b32_e32 v104, v4
	v_mov_b32_e32 v105, v4
	v_mov_b32_e32 v106, v4
	v_mov_b32_e32 v107, v4
	v_mov_b32_e32 v116, v4
	v_mov_b32_e32 v117, v4
	v_mov_b32_e32 v118, v4
	v_mov_b32_e32 v119, v4
	v_mov_b32_e32 v120, v4
	v_mov_b32_e32 v121, v4
	v_mov_b32_e32 v122, v4
	v_mov_b32_e32 v123, v4
	v_mov_b32_e32 v76, v4
	v_mov_b32_e32 v77, v4
	v_mov_b32_e32 v78, v4
	v_mov_b32_e32 v79, v4
	v_mov_b32_e32 v80, v4
	v_mov_b32_e32 v81, v4
	v_mov_b32_e32 v82, v4
	v_mov_b32_e32 v83, v4
	v_mov_b32_e32 v92, v4
	v_mov_b32_e32 v93, v4
	v_mov_b32_e32 v94, v4
	v_mov_b32_e32 v95, v4
	v_mov_b32_e32 v96, v4
	v_mov_b32_e32 v97, v4
	v_mov_b32_e32 v98, v4
	v_mov_b32_e32 v99, v4
	v_mov_b32_e32 v108, v4
	v_mov_b32_e32 v109, v4
	v_mov_b32_e32 v110, v4
	v_mov_b32_e32 v111, v4
	v_mov_b32_e32 v112, v4
	v_mov_b32_e32 v113, v4
	v_mov_b32_e32 v114, v4
	v_mov_b32_e32 v115, v4
	v_mov_b32_e32 v124, v4
	v_mov_b32_e32 v125, v4
	v_mov_b32_e32 v126, v4
	v_mov_b32_e32 v127, v4
	v_mov_b32_e32 v128, v4
	v_mov_b32_e32 v129, v4
	v_mov_b32_e32 v130, v4
	v_mov_b32_e32 v131, v4
	s_andn2_b64 vcc, exec, s[4:5]
	s_cbranch_vccnz .LBB0_1363
